# GEMM K-loops: 3 of 6 LDS-DMA issues of seg2/seg4 moved into the wave's own MFMA block (vmcnt recounted)
# speedup vs baseline: 1.0074x; 1.0074x over previous
.Lwe_0:
	s_waitcnt lgkmcnt(0)
	s_barrier
	s_setprio 1
	s_waitcnt lgkmcnt(0)
	v_mfma_f32_16x16x32_bf16 v[126:129], v[158:161], v[190:193], v[126:129]
	v_mfma_f32_16x16x32_bf16 v[122:125], v[166:169], v[190:193], v[122:125]
	v_mfma_f32_16x16x32_bf16 v[118:121], v[158:161], v[198:201], v[118:121]
	v_mfma_f32_16x16x32_bf16 v[110:113], v[166:169], v[198:201], v[110:113]
	v_mfma_f32_16x16x32_bf16 v[102:105], v[158:161], v[206:209], v[102:105]
	v_mfma_f32_16x16x32_bf16 v[94:97], v[166:169], v[206:209], v[94:97]
	v_mfma_f32_16x16x32_bf16 v[86:89], v[158:161], v[214:217], v[86:89]
	v_mfma_f32_16x16x32_bf16 v[78:81], v[166:169], v[214:217], v[78:81]
	v_mfma_f32_16x16x32_bf16 v[126:129], v[162:165], v[194:197], v[126:129]
	v_mfma_f32_16x16x32_bf16 v[122:125], v[170:173], v[194:197], v[122:125]
	v_mfma_f32_16x16x32_bf16 v[118:121], v[162:165], v[202:205], v[118:121]
	v_mfma_f32_16x16x32_bf16 v[110:113], v[170:173], v[202:205], v[110:113]
	v_mfma_f32_16x16x32_bf16 v[102:105], v[162:165], v[210:213], v[102:105]
	v_mfma_f32_16x16x32_bf16 v[94:97], v[170:173], v[210:213], v[94:97]
	v_mfma_f32_16x16x32_bf16 v[86:89], v[162:165], v[218:221], v[86:89]
	v_mfma_f32_16x16x32_bf16 v[78:81], v[170:173], v[218:221], v[78:81]
	s_setprio 0
	s_setprio 1
	v_mfma_f32_16x16x32_bf16 v[114:117], v[174:177], v[190:193], v[114:117]
	v_mfma_f32_16x16x32_bf16 v[106:109], v[182:185], v[190:193], v[106:109]
	v_mfma_f32_16x16x32_bf16 v[98:101], v[174:177], v[198:201], v[98:101]
	v_mfma_f32_16x16x32_bf16 v[90:93], v[182:185], v[198:201], v[90:93]
	v_mfma_f32_16x16x32_bf16 v[82:85], v[174:177], v[206:209], v[82:85]
	v_mfma_f32_16x16x32_bf16 v[74:77], v[182:185], v[206:209], v[74:77]
	v_mfma_f32_16x16x32_bf16 v[70:73], v[174:177], v[214:217], v[70:73]
	v_mfma_f32_16x16x32_bf16 v[66:69], v[182:185], v[214:217], v[66:69]
	v_mfma_f32_16x16x32_bf16 v[114:117], v[178:181], v[194:197], v[114:117]
	v_mfma_f32_16x16x32_bf16 v[106:109], v[186:189], v[194:197], v[106:109]
	v_mfma_f32_16x16x32_bf16 v[98:101], v[178:181], v[202:205], v[98:101]
	v_mfma_f32_16x16x32_bf16 v[90:93], v[186:189], v[202:205], v[90:93]
	v_mfma_f32_16x16x32_bf16 v[82:85], v[178:181], v[210:213], v[82:85]
	v_mfma_f32_16x16x32_bf16 v[74:77], v[186:189], v[210:213], v[74:77]
	v_mfma_f32_16x16x32_bf16 v[70:73], v[178:181], v[218:221], v[70:73]
	v_mfma_f32_16x16x32_bf16 v[66:69], v[186:189], v[218:221], v[66:69]
	s_setprio 0
	s_barrier
	s_add_i32 s68, s58, s46
	v_lshl_add_u64 v[222:223], s[40:41], 0, v[134:135]
	s_mov_b32 m0, s68
	ds_read_b128 v[190:193], v156 offset:16384
	ds_read_b128 v[194:197], v156 offset:17408
	ds_read_b128 v[198:201], v156 offset:18432
	ds_read_b128 v[202:205], v156 offset:19456
	ds_read_b128 v[206:209], v156 offset:20480
	ds_read_b128 v[210:213], v156 offset:21504
	ds_read_b128 v[214:217], v156 offset:22528
	ds_read_b128 v[218:221], v156 offset:23552
	global_load_lds_dwordx4 v[222:223], off
	s_add_i32 m0, s68, 0x2000
	s_add_u32 s68, s40, 0x80000
	v_lshl_add_u64 v[224:225], s[40:41], 0, v[130:131]
	s_addc_u32 s69, s41, 0
	s_add_i32 s71, s59, s46
	global_load_lds_dwordx4 v[224:225], off
	v_lshl_add_u64 v[226:227], s[68:69], 0, v[134:135]
	s_mov_b32 m0, s71
	v_lshl_add_u64 v[228:229], s[42:43], 0, v[132:133]
	global_load_lds_dwordx4 v[226:227], off
	s_cmp_eq_u32 s70, 0
	s_cbranch_scc1 .Lw8_1
	s_waitcnt vmcnt(21)
	s_branch .Lwe_1
.Lw8_1:
	s_waitcnt vmcnt(5)
.Lwe_1:
	s_waitcnt lgkmcnt(0)
	s_barrier
	s_setprio 1
	s_waitcnt lgkmcnt(0)
	v_mfma_f32_16x16x32_bf16 v[62:65], v[158:161], v[190:193], v[62:65]
	v_mfma_f32_16x16x32_bf16 v[58:61], v[166:169], v[190:193], v[58:61]
	v_lshl_add_u64 v[226:227], s[68:69], 0, v[130:131]
	s_add_i32 m0, s71, 0x2000
	s_nop 0
	global_load_lds_dwordx4 v[226:227], off
	v_mfma_f32_16x16x32_bf16 v[54:57], v[158:161], v[198:201], v[54:57]
	v_mfma_f32_16x16x32_bf16 v[46:49], v[166:169], v[198:201], v[46:49]
	v_mfma_f32_16x16x32_bf16 v[38:41], v[158:161], v[206:209], v[38:41]
	v_mfma_f32_16x16x32_bf16 v[30:33], v[166:169], v[206:209], v[30:33]
	v_mfma_f32_16x16x32_bf16 v[22:25], v[158:161], v[214:217], v[22:25]
	v_mfma_f32_16x16x32_bf16 v[14:17], v[166:169], v[214:217], v[14:17]
	v_mfma_f32_16x16x32_bf16 v[62:65], v[162:165], v[194:197], v[62:65]
	v_mfma_f32_16x16x32_bf16 v[58:61], v[170:173], v[194:197], v[58:61]
	v_lshl_add_u64 v[226:227], s[42:43], 0, v[136:137]
	s_mov_b32 m0, s49
	s_nop 0
	global_load_lds_dwordx4 v[226:227], off
	v_mfma_f32_16x16x32_bf16 v[54:57], v[162:165], v[202:205], v[54:57]
	v_mfma_f32_16x16x32_bf16 v[46:49], v[170:173], v[202:205], v[46:49]
	v_mfma_f32_16x16x32_bf16 v[38:41], v[162:165], v[210:213], v[38:41]
	v_mfma_f32_16x16x32_bf16 v[30:33], v[170:173], v[210:213], v[30:33]
	v_mfma_f32_16x16x32_bf16 v[22:25], v[162:165], v[218:221], v[22:25]
	v_mfma_f32_16x16x32_bf16 v[14:17], v[170:173], v[218:221], v[14:17]
	s_setprio 0
	s_setprio 1
	v_mfma_f32_16x16x32_bf16 v[50:53], v[174:177], v[190:193], v[50:53]
	v_mfma_f32_16x16x32_bf16 v[42:45], v[182:185], v[190:193], v[42:45]
	s_mov_b32 m0, s50
	s_nop 0
	global_load_lds_dwordx4 v[228:229], off
	v_mfma_f32_16x16x32_bf16 v[34:37], v[174:177], v[198:201], v[34:37]
	v_mfma_f32_16x16x32_bf16 v[26:29], v[182:185], v[198:201], v[26:29]
	v_mfma_f32_16x16x32_bf16 v[18:21], v[174:177], v[206:209], v[18:21]
	v_mfma_f32_16x16x32_bf16 v[10:13], v[182:185], v[206:209], v[10:13]
	v_mfma_f32_16x16x32_bf16 v[6:9], v[174:177], v[214:217], v[6:9]
	v_mfma_f32_16x16x32_bf16 v[2:5], v[182:185], v[214:217], v[2:5]
	v_mfma_f32_16x16x32_bf16 v[50:53], v[178:181], v[194:197], v[50:53]
	v_mfma_f32_16x16x32_bf16 v[42:45], v[186:189], v[194:197], v[42:45]
	v_mfma_f32_16x16x32_bf16 v[34:37], v[178:181], v[202:205], v[34:37]
	v_mfma_f32_16x16x32_bf16 v[26:29], v[186:189], v[202:205], v[26:29]
	v_mfma_f32_16x16x32_bf16 v[18:21], v[178:181], v[210:213], v[18:21]
	v_mfma_f32_16x16x32_bf16 v[10:13], v[186:189], v[210:213], v[10:13]
	v_mfma_f32_16x16x32_bf16 v[6:9], v[178:181], v[218:221], v[6:9]
	v_mfma_f32_16x16x32_bf16 v[2:5], v[186:189], v[218:221], v[2:5]
	s_setprio 0
	s_barrier
	s_add_i32 s68, 0, 0x18000
	v_add_u32_e32 v157, s68, v150
	s_add_i32 s69, 0, 0x1c000
	ds_read_b128 v[158:161], v157
	ds_read_b128 v[162:165], v157 offset:1024
	ds_read_b128 v[166:169], v157 offset:2048
	ds_read_b128 v[170:173], v157 offset:3072
	v_add_u32_e32 v157, s69, v150
	ds_read_b128 v[174:177], v157
	ds_read_b128 v[178:181], v157 offset:1024
	ds_read_b128 v[182:185], v157 offset:2048
	ds_read_b128 v[186:189], v157 offset:3072
	s_add_u32 s42, s42, 0x80000
	s_addc_u32 s43, s43, 0
	s_mov_b32 m0, s51
	v_lshl_add_u64 v[230:231], s[42:43], 0, v[136:137]
	ds_read_b128 v[190:193], v156 offset:32768
	ds_read_b128 v[194:197], v156 offset:33792
	ds_read_b128 v[198:201], v156 offset:34816
	ds_read_b128 v[202:205], v156 offset:35840
	ds_read_b128 v[206:209], v156 offset:36864
	ds_read_b128 v[210:213], v156 offset:37888
	ds_read_b128 v[214:217], v156 offset:38912
	ds_read_b128 v[218:221], v156 offset:39936
	global_load_lds_dwordx4 v[230:231], off
	v_lshl_add_u64 v[230:231], s[42:43], 0, v[132:133]
	s_mov_b32 m0, s52
	s_nop 0
	global_load_lds_dwordx4 v[230:231], off
	s_waitcnt vmcnt(8)
	s_waitcnt lgkmcnt(0)
	s_barrier
	s_setprio 1
	s_waitcnt lgkmcnt(0)
	v_mfma_f32_16x16x32_bf16 v[126:129], v[158:161], v[190:193], v[126:129]
	v_mfma_f32_16x16x32_bf16 v[122:125], v[166:169], v[190:193], v[122:125]
	v_mfma_f32_16x16x32_bf16 v[118:121], v[158:161], v[198:201], v[118:121]
	v_mfma_f32_16x16x32_bf16 v[110:113], v[166:169], v[198:201], v[110:113]
	v_mfma_f32_16x16x32_bf16 v[102:105], v[158:161], v[206:209], v[102:105]
	v_mfma_f32_16x16x32_bf16 v[94:97], v[166:169], v[206:209], v[94:97]
	v_mfma_f32_16x16x32_bf16 v[86:89], v[158:161], v[214:217], v[86:89]
	v_mfma_f32_16x16x32_bf16 v[78:81], v[166:169], v[214:217], v[78:81]
	v_mfma_f32_16x16x32_bf16 v[126:129], v[162:165], v[194:197], v[126:129]
	v_mfma_f32_16x16x32_bf16 v[122:125], v[170:173], v[194:197], v[122:125]
	v_mfma_f32_16x16x32_bf16 v[118:121], v[162:165], v[202:205], v[118:121]
	v_mfma_f32_16x16x32_bf16 v[110:113], v[170:173], v[202:205], v[110:113]
	v_mfma_f32_16x16x32_bf16 v[102:105], v[162:165], v[210:213], v[102:105]
	v_mfma_f32_16x16x32_bf16 v[94:97], v[170:173], v[210:213], v[94:97]
	v_mfma_f32_16x16x32_bf16 v[86:89], v[162:165], v[218:221], v[86:89]
	v_mfma_f32_16x16x32_bf16 v[78:81], v[170:173], v[218:221], v[78:81]
	s_setprio 0
	s_setprio 1
	v_mfma_f32_16x16x32_bf16 v[114:117], v[174:177], v[190:193], v[114:117]
	v_mfma_f32_16x16x32_bf16 v[106:109], v[182:185], v[190:193], v[106:109]
	v_mfma_f32_16x16x32_bf16 v[98:101], v[174:177], v[198:201], v[98:101]
	v_mfma_f32_16x16x32_bf16 v[90:93], v[182:185], v[198:201], v[90:93]
	v_mfma_f32_16x16x32_bf16 v[82:85], v[174:177], v[206:209], v[82:85]
	v_mfma_f32_16x16x32_bf16 v[74:77], v[182:185], v[206:209], v[74:77]
	v_mfma_f32_16x16x32_bf16 v[70:73], v[174:177], v[214:217], v[70:73]
	v_mfma_f32_16x16x32_bf16 v[66:69], v[182:185], v[214:217], v[66:69]
	v_mfma_f32_16x16x32_bf16 v[114:117], v[178:181], v[194:197], v[114:117]
	v_mfma_f32_16x16x32_bf16 v[106:109], v[186:189], v[194:197], v[106:109]
	v_mfma_f32_16x16x32_bf16 v[98:101], v[178:181], v[202:205], v[98:101]
	v_mfma_f32_16x16x32_bf16 v[90:93], v[186:189], v[202:205], v[90:93]
	v_mfma_f32_16x16x32_bf16 v[82:85], v[178:181], v[210:213], v[82:85]
	v_mfma_f32_16x16x32_bf16 v[74:77], v[186:189], v[210:213], v[74:77]
	v_mfma_f32_16x16x32_bf16 v[70:73], v[178:181], v[218:221], v[70:73]
	v_mfma_f32_16x16x32_bf16 v[66:69], v[186:189], v[218:221], v[66:69]
	s_setprio 0
	s_barrier
	s_add_i32 s42, s68, s46
	v_lshl_add_u64 v[222:223], v[222:223], 0, s[12:13]
	s_mov_b32 m0, s42
	ds_read_b128 v[190:193], v156 offset:49152
	ds_read_b128 v[194:197], v156 offset:50176
	ds_read_b128 v[198:201], v156 offset:51200
	ds_read_b128 v[202:205], v156 offset:52224
	ds_read_b128 v[206:209], v156 offset:53248
	ds_read_b128 v[210:213], v156 offset:54272
	ds_read_b128 v[214:217], v156 offset:55296
	ds_read_b128 v[218:221], v156 offset:56320
	global_load_lds_dwordx4 v[222:223], off
	s_add_i32 m0, s42, 0x2000
	s_add_u32 s40, s40, 0x80080
	v_lshl_add_u64 v[222:223], v[224:225], 0, s[12:13]
	s_addc_u32 s41, s41, 0
	s_add_i32 s42, s69, s46
	global_load_lds_dwordx4 v[222:223], off
	v_lshl_add_u64 v[222:223], s[40:41], 0, v[134:135]
	s_mov_b32 m0, s42
	s_nop 0
	global_load_lds_dwordx4 v[222:223], off
	s_waitcnt vmcnt(5)
	s_waitcnt lgkmcnt(0)
	s_barrier
	s_setprio 1
	s_waitcnt lgkmcnt(0)
	v_mfma_f32_16x16x32_bf16 v[62:65], v[158:161], v[190:193], v[62:65]
	v_mfma_f32_16x16x32_bf16 v[58:61], v[166:169], v[190:193], v[58:61]
	v_lshl_add_u64 v[222:223], s[40:41], 0, v[130:131]
	s_add_i32 m0, s42, 0x2000
	s_nop 0
	global_load_lds_dwordx4 v[222:223], off
	v_mfma_f32_16x16x32_bf16 v[54:57], v[158:161], v[198:201], v[54:57]
	v_mfma_f32_16x16x32_bf16 v[46:49], v[166:169], v[198:201], v[46:49]
	v_mfma_f32_16x16x32_bf16 v[38:41], v[158:161], v[206:209], v[38:41]
	v_mfma_f32_16x16x32_bf16 v[30:33], v[166:169], v[206:209], v[30:33]
	v_mfma_f32_16x16x32_bf16 v[22:25], v[158:161], v[214:217], v[22:25]
	v_mfma_f32_16x16x32_bf16 v[14:17], v[166:169], v[214:217], v[14:17]
	v_mfma_f32_16x16x32_bf16 v[62:65], v[162:165], v[194:197], v[62:65]
	v_mfma_f32_16x16x32_bf16 v[58:61], v[170:173], v[194:197], v[58:61]
	v_lshl_add_u64 v[222:223], v[226:227], 0, s[12:13]
	s_mov_b32 m0, s54
	s_nop 0
	global_load_lds_dwordx4 v[222:223], off
	v_mfma_f32_16x16x32_bf16 v[54:57], v[162:165], v[202:205], v[54:57]
	v_mfma_f32_16x16x32_bf16 v[46:49], v[170:173], v[202:205], v[46:49]
	v_mfma_f32_16x16x32_bf16 v[38:41], v[162:165], v[210:213], v[38:41]
	v_mfma_f32_16x16x32_bf16 v[30:33], v[170:173], v[210:213], v[30:33]
	v_mfma_f32_16x16x32_bf16 v[22:25], v[162:165], v[218:221], v[22:25]
	v_mfma_f32_16x16x32_bf16 v[14:17], v[170:173], v[218:221], v[14:17]
	s_setprio 0
	s_setprio 1
	v_mfma_f32_16x16x32_bf16 v[50:53], v[174:177], v[190:193], v[50:53]
	v_mfma_f32_16x16x32_bf16 v[42:45], v[182:185], v[190:193], v[42:45]
	v_lshl_add_u64 v[222:223], v[228:229], 0, s[12:13]
	s_mov_b32 m0, s55
	s_nop 0
	global_load_lds_dwordx4 v[222:223], off
	v_mfma_f32_16x16x32_bf16 v[34:37], v[174:177], v[198:201], v[34:37]
	v_mfma_f32_16x16x32_bf16 v[26:29], v[182:185], v[198:201], v[26:29]
	v_mfma_f32_16x16x32_bf16 v[18:21], v[174:177], v[206:209], v[18:21]
	v_mfma_f32_16x16x32_bf16 v[10:13], v[182:185], v[206:209], v[10:13]
	v_mfma_f32_16x16x32_bf16 v[6:9], v[174:177], v[214:217], v[6:9]
	v_mfma_f32_16x16x32_bf16 v[2:5], v[182:185], v[214:217], v[2:5]
	v_mfma_f32_16x16x32_bf16 v[50:53], v[178:181], v[194:197], v[50:53]
	v_mfma_f32_16x16x32_bf16 v[42:45], v[186:189], v[194:197], v[42:45]
	v_mfma_f32_16x16x32_bf16 v[34:37], v[178:181], v[202:205], v[34:37]
	v_mfma_f32_16x16x32_bf16 v[26:29], v[186:189], v[202:205], v[26:29]
	v_mfma_f32_16x16x32_bf16 v[18:21], v[178:181], v[210:213], v[18:21]
	v_mfma_f32_16x16x32_bf16 v[10:13], v[186:189], v[210:213], v[10:13]
	v_mfma_f32_16x16x32_bf16 v[6:9], v[178:181], v[218:221], v[6:9]
	v_mfma_f32_16x16x32_bf16 v[2:5], v[186:189], v[218:221], v[2:5]
	s_setprio 0
	s_barrier
	s_add_i32 s67, s67, 2
	s_add_u32 s38, s38, 0x100
	s_addc_u32 s39, s39, 0
	s_cmp_gt_u32 s67, 29
	s_cbranch_scc0 .LBB0_346
	s_and_b64 vcc, exec, s[14:15]
	s_cbranch_vccnz .LBB0_351
	s_mov_b64 s[30:31], -1
	s_and_b64 vcc, exec, s[34:35]
	s_cbranch_vccnz .LBB0_352

.Lwe_2:
	s_waitcnt lgkmcnt(0)
	s_barrier
	s_setprio 1
	s_waitcnt lgkmcnt(0)
	v_mfma_f32_16x16x32_bf16 v[126:129], v[158:161], v[190:193], v[126:129]
	v_mfma_f32_16x16x32_bf16 v[122:125], v[166:169], v[190:193], v[122:125]
	v_mfma_f32_16x16x32_bf16 v[110:113], v[158:161], v[198:201], v[110:113]
	v_mfma_f32_16x16x32_bf16 v[106:109], v[166:169], v[198:201], v[106:109]
	v_mfma_f32_16x16x32_bf16 v[94:97], v[158:161], v[206:209], v[94:97]
	v_mfma_f32_16x16x32_bf16 v[90:93], v[166:169], v[206:209], v[90:93]
	v_mfma_f32_16x16x32_bf16 v[78:81], v[158:161], v[214:217], v[78:81]
	v_mfma_f32_16x16x32_bf16 v[74:77], v[166:169], v[214:217], v[74:77]
	v_mfma_f32_16x16x32_bf16 v[126:129], v[162:165], v[194:197], v[126:129]
	v_mfma_f32_16x16x32_bf16 v[122:125], v[170:173], v[194:197], v[122:125]
	v_mfma_f32_16x16x32_bf16 v[110:113], v[162:165], v[202:205], v[110:113]
	v_mfma_f32_16x16x32_bf16 v[106:109], v[170:173], v[202:205], v[106:109]
	v_mfma_f32_16x16x32_bf16 v[94:97], v[162:165], v[210:213], v[94:97]
	v_mfma_f32_16x16x32_bf16 v[90:93], v[170:173], v[210:213], v[90:93]
	v_mfma_f32_16x16x32_bf16 v[78:81], v[162:165], v[218:221], v[78:81]
	v_mfma_f32_16x16x32_bf16 v[74:77], v[170:173], v[218:221], v[74:77]
	s_setprio 0
	s_setprio 1
	v_mfma_f32_16x16x32_bf16 v[118:121], v[174:177], v[190:193], v[118:121]
	v_mfma_f32_16x16x32_bf16 v[114:117], v[182:185], v[190:193], v[114:117]
	v_mfma_f32_16x16x32_bf16 v[102:105], v[174:177], v[198:201], v[102:105]
	v_mfma_f32_16x16x32_bf16 v[98:101], v[182:185], v[198:201], v[98:101]
	v_mfma_f32_16x16x32_bf16 v[86:89], v[174:177], v[206:209], v[86:89]
	v_mfma_f32_16x16x32_bf16 v[82:85], v[182:185], v[206:209], v[82:85]
	v_mfma_f32_16x16x32_bf16 v[70:73], v[174:177], v[214:217], v[70:73]
	v_mfma_f32_16x16x32_bf16 v[66:69], v[182:185], v[214:217], v[66:69]
	v_mfma_f32_16x16x32_bf16 v[118:121], v[178:181], v[194:197], v[118:121]
	v_mfma_f32_16x16x32_bf16 v[114:117], v[186:189], v[194:197], v[114:117]
	v_mfma_f32_16x16x32_bf16 v[102:105], v[178:181], v[202:205], v[102:105]
	v_mfma_f32_16x16x32_bf16 v[98:101], v[186:189], v[202:205], v[98:101]
	v_mfma_f32_16x16x32_bf16 v[86:89], v[178:181], v[210:213], v[86:89]
	v_mfma_f32_16x16x32_bf16 v[82:85], v[186:189], v[210:213], v[82:85]
	v_mfma_f32_16x16x32_bf16 v[70:73], v[178:181], v[218:221], v[70:73]
	v_mfma_f32_16x16x32_bf16 v[66:69], v[186:189], v[218:221], v[66:69]
	s_setprio 0
	s_barrier
	s_add_i32 s60, s50, s41
	v_lshl_add_u64 v[150:151], s[30:31], 0, v[132:133]
	s_mov_b32 m0, s60
	ds_read_b128 v[190:193], v157 offset:16384
	ds_read_b128 v[194:197], v157 offset:17408
	ds_read_b128 v[198:201], v157 offset:18432
	ds_read_b128 v[202:205], v157 offset:19456
	ds_read_b128 v[206:209], v157 offset:20480
	ds_read_b128 v[210:213], v157 offset:21504
	ds_read_b128 v[214:217], v157 offset:22528
	ds_read_b128 v[218:221], v157 offset:23552
	global_load_lds_dwordx4 v[150:151], off
	s_add_i32 m0, s60, 0x2000
	s_add_u32 s60, s30, 0x40000
	v_lshl_add_u64 v[222:223], s[30:31], 0, v[136:137]
	s_addc_u32 s61, s31, 0
	s_add_i32 s62, s51, s41
	global_load_lds_dwordx4 v[222:223], off
	v_lshl_add_u64 v[224:225], s[60:61], 0, v[132:133]
	s_mov_b32 m0, s62
	v_lshl_add_u64 v[226:227], s[34:35], 0, v[134:135]
	global_load_lds_dwordx4 v[224:225], off
	s_cmp_eq_u32 s59, 0
	s_cbranch_scc1 .Lw8_3
	s_waitcnt vmcnt(21)
	s_branch .Lwe_3

.Lwe_3:
	s_waitcnt lgkmcnt(0)
	s_barrier
	s_setprio 1
	s_waitcnt lgkmcnt(0)
	v_mfma_f32_16x16x32_bf16 v[62:65], v[158:161], v[190:193], v[62:65]
	v_mfma_f32_16x16x32_bf16 v[58:61], v[166:169], v[190:193], v[58:61]
	v_lshl_add_u64 v[224:225], s[60:61], 0, v[136:137]
	s_add_i32 m0, s62, 0x2000
	s_nop 0
	global_load_lds_dwordx4 v[224:225], off
	v_mfma_f32_16x16x32_bf16 v[46:49], v[158:161], v[198:201], v[46:49]
	v_mfma_f32_16x16x32_bf16 v[42:45], v[166:169], v[198:201], v[42:45]
	v_mfma_f32_16x16x32_bf16 v[30:33], v[158:161], v[206:209], v[30:33]
	v_mfma_f32_16x16x32_bf16 v[26:29], v[166:169], v[206:209], v[26:29]
	v_mfma_f32_16x16x32_bf16 v[14:17], v[158:161], v[214:217], v[14:17]
	v_mfma_f32_16x16x32_bf16 v[10:13], v[166:169], v[214:217], v[10:13]
	v_mfma_f32_16x16x32_bf16 v[62:65], v[162:165], v[194:197], v[62:65]
	v_mfma_f32_16x16x32_bf16 v[58:61], v[170:173], v[194:197], v[58:61]
	v_lshl_add_u64 v[224:225], s[34:35], 0, v[130:131]
	s_mov_b32 m0, s23
	s_nop 0
	global_load_lds_dwordx4 v[224:225], off
	v_mfma_f32_16x16x32_bf16 v[46:49], v[162:165], v[202:205], v[46:49]
	v_mfma_f32_16x16x32_bf16 v[42:45], v[170:173], v[202:205], v[42:45]
	v_mfma_f32_16x16x32_bf16 v[30:33], v[162:165], v[210:213], v[30:33]
	v_mfma_f32_16x16x32_bf16 v[26:29], v[170:173], v[210:213], v[26:29]
	v_mfma_f32_16x16x32_bf16 v[14:17], v[162:165], v[218:221], v[14:17]
	v_mfma_f32_16x16x32_bf16 v[10:13], v[170:173], v[218:221], v[10:13]
	s_setprio 0
	s_setprio 1
	v_mfma_f32_16x16x32_bf16 v[54:57], v[174:177], v[190:193], v[54:57]
	v_mfma_f32_16x16x32_bf16 v[50:53], v[182:185], v[190:193], v[50:53]
	s_mov_b32 m0, s42
	s_nop 0
	global_load_lds_dwordx4 v[226:227], off
	v_mfma_f32_16x16x32_bf16 v[38:41], v[174:177], v[198:201], v[38:41]
	v_mfma_f32_16x16x32_bf16 v[34:37], v[182:185], v[198:201], v[34:37]
	v_mfma_f32_16x16x32_bf16 v[22:25], v[174:177], v[206:209], v[22:25]
	v_mfma_f32_16x16x32_bf16 v[18:21], v[182:185], v[206:209], v[18:21]
	v_mfma_f32_16x16x32_bf16 v[6:9], v[174:177], v[214:217], v[6:9]
	v_mfma_f32_16x16x32_bf16 v[2:5], v[182:185], v[214:217], v[2:5]
	v_mfma_f32_16x16x32_bf16 v[54:57], v[178:181], v[194:197], v[54:57]
	v_mfma_f32_16x16x32_bf16 v[50:53], v[186:189], v[194:197], v[50:53]
	v_mfma_f32_16x16x32_bf16 v[38:41], v[178:181], v[202:205], v[38:41]
	v_mfma_f32_16x16x32_bf16 v[34:37], v[186:189], v[202:205], v[34:37]
	v_mfma_f32_16x16x32_bf16 v[22:25], v[178:181], v[210:213], v[22:25]
	v_mfma_f32_16x16x32_bf16 v[18:21], v[186:189], v[210:213], v[18:21]
	v_mfma_f32_16x16x32_bf16 v[6:9], v[178:181], v[218:221], v[6:9]
	v_mfma_f32_16x16x32_bf16 v[2:5], v[186:189], v[218:221], v[2:5]
	s_setprio 0
	s_barrier
	s_add_i32 s59, 0, 0x18000
	s_add_i32 s60, 0, 0x1c000
	v_add_u32_e32 v170, s59, v152
	v_add_u32_e32 v186, s60, v152
	ds_read_b128 v[158:161], v170
	ds_read_b128 v[162:165], v170 offset:1024
	ds_read_b128 v[166:169], v170 offset:2048
	ds_read_b128 v[170:173], v170 offset:3072
	ds_read_b128 v[174:177], v186
	ds_read_b128 v[178:181], v186 offset:1024
	ds_read_b128 v[182:185], v186 offset:2048
	ds_read_b128 v[186:189], v186 offset:3072
	s_add_u32 s34, s34, 0x40000
	s_addc_u32 s35, s35, 0
	s_mov_b32 m0, s43
	v_lshl_add_u64 v[228:229], s[34:35], 0, v[130:131]
	ds_read_b128 v[190:193], v157 offset:32768
	ds_read_b128 v[194:197], v157 offset:33792
	ds_read_b128 v[198:201], v157 offset:34816
	ds_read_b128 v[202:205], v157 offset:35840
	ds_read_b128 v[206:209], v157 offset:36864
	ds_read_b128 v[210:213], v157 offset:37888
	ds_read_b128 v[214:217], v157 offset:38912
	ds_read_b128 v[218:221], v157 offset:39936
	global_load_lds_dwordx4 v[228:229], off
	v_lshl_add_u64 v[228:229], s[34:35], 0, v[134:135]
	s_mov_b32 m0, s44
	s_nop 0
	global_load_lds_dwordx4 v[228:229], off
	s_waitcnt vmcnt(8)
	s_waitcnt lgkmcnt(0)
	s_barrier
	s_setprio 1
	s_waitcnt lgkmcnt(0)
	v_mfma_f32_16x16x32_bf16 v[126:129], v[158:161], v[190:193], v[126:129]
	v_mfma_f32_16x16x32_bf16 v[122:125], v[166:169], v[190:193], v[122:125]
	v_mfma_f32_16x16x32_bf16 v[110:113], v[158:161], v[198:201], v[110:113]
	v_mfma_f32_16x16x32_bf16 v[106:109], v[166:169], v[198:201], v[106:109]
	v_mfma_f32_16x16x32_bf16 v[94:97], v[158:161], v[206:209], v[94:97]
	v_mfma_f32_16x16x32_bf16 v[90:93], v[166:169], v[206:209], v[90:93]
	v_mfma_f32_16x16x32_bf16 v[78:81], v[158:161], v[214:217], v[78:81]
	v_mfma_f32_16x16x32_bf16 v[74:77], v[166:169], v[214:217], v[74:77]
	v_mfma_f32_16x16x32_bf16 v[126:129], v[162:165], v[194:197], v[126:129]
	v_mfma_f32_16x16x32_bf16 v[122:125], v[170:173], v[194:197], v[122:125]
	v_mfma_f32_16x16x32_bf16 v[110:113], v[162:165], v[202:205], v[110:113]
	v_mfma_f32_16x16x32_bf16 v[106:109], v[170:173], v[202:205], v[106:109]
	v_mfma_f32_16x16x32_bf16 v[94:97], v[162:165], v[210:213], v[94:97]
	v_mfma_f32_16x16x32_bf16 v[90:93], v[170:173], v[210:213], v[90:93]
	v_mfma_f32_16x16x32_bf16 v[78:81], v[162:165], v[218:221], v[78:81]
	v_mfma_f32_16x16x32_bf16 v[74:77], v[170:173], v[218:221], v[74:77]
	s_setprio 0
	s_setprio 1
	v_mfma_f32_16x16x32_bf16 v[118:121], v[174:177], v[190:193], v[118:121]
	v_mfma_f32_16x16x32_bf16 v[114:117], v[182:185], v[190:193], v[114:117]
	v_mfma_f32_16x16x32_bf16 v[102:105], v[174:177], v[198:201], v[102:105]
	v_mfma_f32_16x16x32_bf16 v[98:101], v[182:185], v[198:201], v[98:101]
	v_mfma_f32_16x16x32_bf16 v[86:89], v[174:177], v[206:209], v[86:89]
	v_mfma_f32_16x16x32_bf16 v[82:85], v[182:185], v[206:209], v[82:85]
	v_mfma_f32_16x16x32_bf16 v[70:73], v[174:177], v[214:217], v[70:73]
	v_mfma_f32_16x16x32_bf16 v[66:69], v[182:185], v[214:217], v[66:69]
	v_mfma_f32_16x16x32_bf16 v[118:121], v[178:181], v[194:197], v[118:121]
	v_mfma_f32_16x16x32_bf16 v[114:117], v[186:189], v[194:197], v[114:117]
	v_mfma_f32_16x16x32_bf16 v[102:105], v[178:181], v[202:205], v[102:105]
	v_mfma_f32_16x16x32_bf16 v[98:101], v[186:189], v[202:205], v[98:101]
	v_mfma_f32_16x16x32_bf16 v[86:89], v[178:181], v[210:213], v[86:89]
	v_mfma_f32_16x16x32_bf16 v[82:85], v[186:189], v[210:213], v[82:85]
	v_mfma_f32_16x16x32_bf16 v[70:73], v[178:181], v[218:221], v[70:73]
	v_mfma_f32_16x16x32_bf16 v[66:69], v[186:189], v[218:221], v[66:69]
	s_setprio 0
	s_barrier
	s_add_i32 s34, s59, s41
	v_lshl_add_u64 v[150:151], v[150:151], 0, s[10:11]
	s_mov_b32 m0, s34
	ds_read_b128 v[190:193], v157 offset:49152
	ds_read_b128 v[194:197], v157 offset:50176
	ds_read_b128 v[198:201], v157 offset:51200
	ds_read_b128 v[202:205], v157 offset:52224
	ds_read_b128 v[206:209], v157 offset:53248
	ds_read_b128 v[210:213], v157 offset:54272
	ds_read_b128 v[214:217], v157 offset:55296
	ds_read_b128 v[218:221], v157 offset:56320
	global_load_lds_dwordx4 v[150:151], off
	s_add_i32 m0, s34, 0x2000
	s_add_u32 s30, s30, 0x40080
	v_lshl_add_u64 v[150:151], v[222:223], 0, s[10:11]
	s_addc_u32 s31, s31, 0
	s_add_i32 s34, s60, s41
	global_load_lds_dwordx4 v[150:151], off
	v_lshl_add_u64 v[150:151], s[30:31], 0, v[132:133]
	s_mov_b32 m0, s34
	s_nop 0
	global_load_lds_dwordx4 v[150:151], off
	s_waitcnt vmcnt(5)
	s_waitcnt lgkmcnt(0)
	s_barrier
	s_setprio 1
	s_waitcnt lgkmcnt(0)
	v_mfma_f32_16x16x32_bf16 v[62:65], v[158:161], v[190:193], v[62:65]
	v_mfma_f32_16x16x32_bf16 v[58:61], v[166:169], v[190:193], v[58:61]
	v_lshl_add_u64 v[150:151], s[30:31], 0, v[136:137]
	s_add_i32 m0, s34, 0x2000
	s_nop 0
	global_load_lds_dwordx4 v[150:151], off
	v_mfma_f32_16x16x32_bf16 v[46:49], v[158:161], v[198:201], v[46:49]
	v_mfma_f32_16x16x32_bf16 v[42:45], v[166:169], v[198:201], v[42:45]
	v_mfma_f32_16x16x32_bf16 v[30:33], v[158:161], v[206:209], v[30:33]
	v_mfma_f32_16x16x32_bf16 v[26:29], v[166:169], v[206:209], v[26:29]
	v_mfma_f32_16x16x32_bf16 v[14:17], v[158:161], v[214:217], v[14:17]
	v_mfma_f32_16x16x32_bf16 v[10:13], v[166:169], v[214:217], v[10:13]
	v_mfma_f32_16x16x32_bf16 v[62:65], v[162:165], v[194:197], v[62:65]
	v_mfma_f32_16x16x32_bf16 v[58:61], v[170:173], v[194:197], v[58:61]
	v_lshl_add_u64 v[150:151], v[224:225], 0, s[10:11]
	s_mov_b32 m0, s46
	s_nop 0
	global_load_lds_dwordx4 v[150:151], off
	v_mfma_f32_16x16x32_bf16 v[46:49], v[162:165], v[202:205], v[46:49]
	v_mfma_f32_16x16x32_bf16 v[42:45], v[170:173], v[202:205], v[42:45]
	v_mfma_f32_16x16x32_bf16 v[30:33], v[162:165], v[210:213], v[30:33]
	v_mfma_f32_16x16x32_bf16 v[26:29], v[170:173], v[210:213], v[26:29]
	v_mfma_f32_16x16x32_bf16 v[14:17], v[162:165], v[218:221], v[14:17]
	v_mfma_f32_16x16x32_bf16 v[10:13], v[170:173], v[218:221], v[10:13]
	s_setprio 0
	s_setprio 1
	v_mfma_f32_16x16x32_bf16 v[54:57], v[174:177], v[190:193], v[54:57]
	v_mfma_f32_16x16x32_bf16 v[50:53], v[182:185], v[190:193], v[50:53]
	v_lshl_add_u64 v[150:151], v[226:227], 0, s[10:11]
	s_mov_b32 m0, s47
	s_nop 0
	global_load_lds_dwordx4 v[150:151], off
	v_mfma_f32_16x16x32_bf16 v[38:41], v[174:177], v[198:201], v[38:41]
	v_mfma_f32_16x16x32_bf16 v[34:37], v[182:185], v[198:201], v[34:37]
	v_mfma_f32_16x16x32_bf16 v[22:25], v[174:177], v[206:209], v[22:25]
	v_mfma_f32_16x16x32_bf16 v[18:21], v[182:185], v[206:209], v[18:21]
	v_mfma_f32_16x16x32_bf16 v[6:9], v[174:177], v[214:217], v[6:9]
	v_mfma_f32_16x16x32_bf16 v[2:5], v[182:185], v[214:217], v[2:5]
	v_mfma_f32_16x16x32_bf16 v[54:57], v[178:181], v[194:197], v[54:57]
	v_mfma_f32_16x16x32_bf16 v[50:53], v[186:189], v[194:197], v[50:53]
	v_mfma_f32_16x16x32_bf16 v[38:41], v[178:181], v[202:205], v[38:41]
	v_mfma_f32_16x16x32_bf16 v[34:37], v[186:189], v[202:205], v[34:37]
	v_mfma_f32_16x16x32_bf16 v[22:25], v[178:181], v[210:213], v[22:25]
	v_mfma_f32_16x16x32_bf16 v[18:21], v[186:189], v[210:213], v[18:21]
	v_mfma_f32_16x16x32_bf16 v[6:9], v[178:181], v[218:221], v[6:9]
	v_mfma_f32_16x16x32_bf16 v[2:5], v[186:189], v[218:221], v[2:5]
	s_setprio 0
	s_barrier
	s_add_i32 s58, s58, 2
	s_add_u32 s28, s28, 0x100
	s_addc_u32 s29, s29, 0
	s_cmp_gt_u32 s58, 13
	s_cbranch_scc0 .LBB0_891
	s_and_b64 vcc, exec, s[12:13]
	s_cbranch_vccz .LBB0_894
	s_barrier

.Lwe_4:
	s_waitcnt lgkmcnt(0)
	s_barrier
	s_setprio 1
	s_waitcnt lgkmcnt(0)
	v_mfma_f32_16x16x32_bf16 v[126:129], v[150:153], v[188:191], v[126:129]
	v_mfma_f32_16x16x32_bf16 v[122:125], v[164:167], v[188:191], v[122:125]
	v_mfma_f32_16x16x32_bf16 v[110:113], v[150:153], v[196:199], v[110:113]
	v_mfma_f32_16x16x32_bf16 v[106:109], v[164:167], v[196:199], v[106:109]
	v_mfma_f32_16x16x32_bf16 v[94:97], v[150:153], v[204:207], v[94:97]
	v_mfma_f32_16x16x32_bf16 v[90:93], v[164:167], v[204:207], v[90:93]
	v_mfma_f32_16x16x32_bf16 v[78:81], v[150:153], v[212:215], v[78:81]
	v_mfma_f32_16x16x32_bf16 v[74:77], v[164:167], v[212:215], v[74:77]
	v_mfma_f32_16x16x32_bf16 v[126:129], v[160:163], v[192:195], v[126:129]
	v_mfma_f32_16x16x32_bf16 v[122:125], v[168:171], v[192:195], v[122:125]
	v_mfma_f32_16x16x32_bf16 v[110:113], v[160:163], v[200:203], v[110:113]
	v_mfma_f32_16x16x32_bf16 v[106:109], v[168:171], v[200:203], v[106:109]
	v_mfma_f32_16x16x32_bf16 v[94:97], v[160:163], v[208:211], v[94:97]
	v_mfma_f32_16x16x32_bf16 v[90:93], v[168:171], v[208:211], v[90:93]
	v_mfma_f32_16x16x32_bf16 v[78:81], v[160:163], v[216:219], v[78:81]
	v_mfma_f32_16x16x32_bf16 v[74:77], v[168:171], v[216:219], v[74:77]
	s_setprio 0
	s_setprio 1
	v_mfma_f32_16x16x32_bf16 v[118:121], v[172:175], v[188:191], v[118:121]
	v_mfma_f32_16x16x32_bf16 v[114:117], v[180:183], v[188:191], v[114:117]
	v_mfma_f32_16x16x32_bf16 v[102:105], v[172:175], v[196:199], v[102:105]
	v_mfma_f32_16x16x32_bf16 v[98:101], v[180:183], v[196:199], v[98:101]
	v_mfma_f32_16x16x32_bf16 v[86:89], v[172:175], v[204:207], v[86:89]
	v_mfma_f32_16x16x32_bf16 v[82:85], v[180:183], v[204:207], v[82:85]
	v_mfma_f32_16x16x32_bf16 v[70:73], v[172:175], v[212:215], v[70:73]
	v_mfma_f32_16x16x32_bf16 v[66:69], v[180:183], v[212:215], v[66:69]
	v_mfma_f32_16x16x32_bf16 v[118:121], v[176:179], v[192:195], v[118:121]
	v_mfma_f32_16x16x32_bf16 v[114:117], v[184:187], v[192:195], v[114:117]
	v_mfma_f32_16x16x32_bf16 v[102:105], v[176:179], v[200:203], v[102:105]
	v_mfma_f32_16x16x32_bf16 v[98:101], v[184:187], v[200:203], v[98:101]
	v_mfma_f32_16x16x32_bf16 v[86:89], v[176:179], v[208:211], v[86:89]
	v_mfma_f32_16x16x32_bf16 v[82:85], v[184:187], v[208:211], v[82:85]
	v_mfma_f32_16x16x32_bf16 v[70:73], v[176:179], v[216:219], v[70:73]
	v_mfma_f32_16x16x32_bf16 v[66:69], v[184:187], v[216:219], v[66:69]
	s_setprio 0
	s_barrier
	s_add_i32 s60, s50, s41
	v_lshl_add_u64 v[220:221], s[30:31], 0, v[132:133]
	s_mov_b32 m0, s60
	ds_read_b128 v[188:191], v159 offset:16384
	ds_read_b128 v[192:195], v159 offset:17408
	ds_read_b128 v[196:199], v159 offset:18432
	ds_read_b128 v[200:203], v159 offset:19456
	ds_read_b128 v[204:207], v159 offset:20480
	ds_read_b128 v[208:211], v159 offset:21504
	ds_read_b128 v[212:215], v159 offset:22528
	ds_read_b128 v[216:219], v159 offset:23552
	global_load_lds_dwordx4 v[220:221], off
	s_add_i32 m0, s60, 0x2000
	s_add_u32 s60, s30, 0x40000
	v_lshl_add_u64 v[222:223], s[30:31], 0, v[136:137]
	s_addc_u32 s61, s31, 0
	s_add_i32 s62, s51, s41
	global_load_lds_dwordx4 v[222:223], off
	v_lshl_add_u64 v[224:225], s[60:61], 0, v[132:133]
	s_mov_b32 m0, s62
	v_lshl_add_u64 v[226:227], s[34:35], 0, v[134:135]
	global_load_lds_dwordx4 v[224:225], off
	s_cmp_eq_u32 s59, 0
	s_cbranch_scc1 .Lw8_5
	s_waitcnt vmcnt(21)
	s_branch .Lwe_5

.Lwe_5:
	s_waitcnt lgkmcnt(0)
	s_barrier
	s_setprio 1
	s_waitcnt lgkmcnt(0)
	v_mfma_f32_16x16x32_bf16 v[62:65], v[150:153], v[188:191], v[62:65]
	v_mfma_f32_16x16x32_bf16 v[58:61], v[164:167], v[188:191], v[58:61]
	v_lshl_add_u64 v[224:225], s[60:61], 0, v[136:137]
	s_add_i32 m0, s62, 0x2000
	s_nop 0
	global_load_lds_dwordx4 v[224:225], off
	v_mfma_f32_16x16x32_bf16 v[46:49], v[150:153], v[196:199], v[46:49]
	v_mfma_f32_16x16x32_bf16 v[42:45], v[164:167], v[196:199], v[42:45]
	v_mfma_f32_16x16x32_bf16 v[30:33], v[150:153], v[204:207], v[30:33]
	v_mfma_f32_16x16x32_bf16 v[26:29], v[164:167], v[204:207], v[26:29]
	v_mfma_f32_16x16x32_bf16 v[14:17], v[150:153], v[212:215], v[14:17]
	v_mfma_f32_16x16x32_bf16 v[10:13], v[164:167], v[212:215], v[10:13]
	v_mfma_f32_16x16x32_bf16 v[62:65], v[160:163], v[192:195], v[62:65]
	v_mfma_f32_16x16x32_bf16 v[58:61], v[168:171], v[192:195], v[58:61]
	v_lshl_add_u64 v[224:225], s[34:35], 0, v[130:131]
	s_mov_b32 m0, s23
	s_nop 0
	global_load_lds_dwordx4 v[224:225], off
	v_mfma_f32_16x16x32_bf16 v[46:49], v[160:163], v[200:203], v[46:49]
	v_mfma_f32_16x16x32_bf16 v[42:45], v[168:171], v[200:203], v[42:45]
	v_mfma_f32_16x16x32_bf16 v[30:33], v[160:163], v[208:211], v[30:33]
	v_mfma_f32_16x16x32_bf16 v[26:29], v[168:171], v[208:211], v[26:29]
	v_mfma_f32_16x16x32_bf16 v[14:17], v[160:163], v[216:219], v[14:17]
	v_mfma_f32_16x16x32_bf16 v[10:13], v[168:171], v[216:219], v[10:13]
	s_setprio 0
	s_setprio 1
	v_mfma_f32_16x16x32_bf16 v[54:57], v[172:175], v[188:191], v[54:57]
	v_mfma_f32_16x16x32_bf16 v[50:53], v[180:183], v[188:191], v[50:53]
	s_mov_b32 m0, s42
	s_nop 0
	global_load_lds_dwordx4 v[226:227], off
	v_mfma_f32_16x16x32_bf16 v[38:41], v[172:175], v[196:199], v[38:41]
	v_mfma_f32_16x16x32_bf16 v[34:37], v[180:183], v[196:199], v[34:37]
	v_mfma_f32_16x16x32_bf16 v[22:25], v[172:175], v[204:207], v[22:25]
	v_mfma_f32_16x16x32_bf16 v[18:21], v[180:183], v[204:207], v[18:21]
	v_mfma_f32_16x16x32_bf16 v[6:9], v[172:175], v[212:215], v[6:9]
	v_mfma_f32_16x16x32_bf16 v[2:5], v[180:183], v[212:215], v[2:5]
	v_mfma_f32_16x16x32_bf16 v[54:57], v[176:179], v[192:195], v[54:57]
	v_mfma_f32_16x16x32_bf16 v[50:53], v[184:187], v[192:195], v[50:53]
	v_mfma_f32_16x16x32_bf16 v[38:41], v[176:179], v[200:203], v[38:41]
	v_mfma_f32_16x16x32_bf16 v[34:37], v[184:187], v[200:203], v[34:37]
	v_mfma_f32_16x16x32_bf16 v[22:25], v[176:179], v[208:211], v[22:25]
	v_mfma_f32_16x16x32_bf16 v[18:21], v[184:187], v[208:211], v[18:21]
	v_mfma_f32_16x16x32_bf16 v[6:9], v[176:179], v[216:219], v[6:9]
	v_mfma_f32_16x16x32_bf16 v[2:5], v[184:187], v[216:219], v[2:5]
	s_setprio 0
	s_barrier
	s_add_i32 s59, 0, 0x18000
	s_add_i32 s60, 0, 0x1c000
	v_add_u32_e32 v168, s59, v155
	v_add_u32_e32 v184, s60, v155
	ds_read_b128 v[150:153], v168
	ds_read_b128 v[160:163], v168 offset:1024
	ds_read_b128 v[164:167], v168 offset:2048
	ds_read_b128 v[168:171], v168 offset:3072
	ds_read_b128 v[172:175], v184
	ds_read_b128 v[176:179], v184 offset:1024
	ds_read_b128 v[180:183], v184 offset:2048
	ds_read_b128 v[184:187], v184 offset:3072
	s_add_u32 s34, s34, 0x40000
	s_addc_u32 s35, s35, 0
	s_mov_b32 m0, s43
	v_lshl_add_u64 v[228:229], s[34:35], 0, v[130:131]
	ds_read_b128 v[188:191], v159 offset:32768
	ds_read_b128 v[192:195], v159 offset:33792
	ds_read_b128 v[196:199], v159 offset:34816
	ds_read_b128 v[200:203], v159 offset:35840
	ds_read_b128 v[204:207], v159 offset:36864
	ds_read_b128 v[208:211], v159 offset:37888
	ds_read_b128 v[212:215], v159 offset:38912
	ds_read_b128 v[216:219], v159 offset:39936
	global_load_lds_dwordx4 v[228:229], off
	v_lshl_add_u64 v[228:229], s[34:35], 0, v[134:135]
	s_mov_b32 m0, s44
	s_nop 0
	global_load_lds_dwordx4 v[228:229], off
	s_waitcnt vmcnt(8)
	s_waitcnt lgkmcnt(0)
	s_barrier
	s_setprio 1
	s_waitcnt lgkmcnt(0)
	v_mfma_f32_16x16x32_bf16 v[126:129], v[150:153], v[188:191], v[126:129]
	v_mfma_f32_16x16x32_bf16 v[122:125], v[164:167], v[188:191], v[122:125]
	v_mfma_f32_16x16x32_bf16 v[110:113], v[150:153], v[196:199], v[110:113]
	v_mfma_f32_16x16x32_bf16 v[106:109], v[164:167], v[196:199], v[106:109]
	v_mfma_f32_16x16x32_bf16 v[94:97], v[150:153], v[204:207], v[94:97]
	v_mfma_f32_16x16x32_bf16 v[90:93], v[164:167], v[204:207], v[90:93]
	v_mfma_f32_16x16x32_bf16 v[78:81], v[150:153], v[212:215], v[78:81]
	v_mfma_f32_16x16x32_bf16 v[74:77], v[164:167], v[212:215], v[74:77]
	v_mfma_f32_16x16x32_bf16 v[126:129], v[160:163], v[192:195], v[126:129]
	v_mfma_f32_16x16x32_bf16 v[122:125], v[168:171], v[192:195], v[122:125]
	v_mfma_f32_16x16x32_bf16 v[110:113], v[160:163], v[200:203], v[110:113]
	v_mfma_f32_16x16x32_bf16 v[106:109], v[168:171], v[200:203], v[106:109]
	v_mfma_f32_16x16x32_bf16 v[94:97], v[160:163], v[208:211], v[94:97]
	v_mfma_f32_16x16x32_bf16 v[90:93], v[168:171], v[208:211], v[90:93]
	v_mfma_f32_16x16x32_bf16 v[78:81], v[160:163], v[216:219], v[78:81]
	v_mfma_f32_16x16x32_bf16 v[74:77], v[168:171], v[216:219], v[74:77]
	s_setprio 0
	s_setprio 1
	v_mfma_f32_16x16x32_bf16 v[118:121], v[172:175], v[188:191], v[118:121]
	v_mfma_f32_16x16x32_bf16 v[114:117], v[180:183], v[188:191], v[114:117]
	v_mfma_f32_16x16x32_bf16 v[102:105], v[172:175], v[196:199], v[102:105]
	v_mfma_f32_16x16x32_bf16 v[98:101], v[180:183], v[196:199], v[98:101]
	v_mfma_f32_16x16x32_bf16 v[86:89], v[172:175], v[204:207], v[86:89]
	v_mfma_f32_16x16x32_bf16 v[82:85], v[180:183], v[204:207], v[82:85]
	v_mfma_f32_16x16x32_bf16 v[70:73], v[172:175], v[212:215], v[70:73]
	v_mfma_f32_16x16x32_bf16 v[66:69], v[180:183], v[212:215], v[66:69]
	v_mfma_f32_16x16x32_bf16 v[118:121], v[176:179], v[192:195], v[118:121]
	v_mfma_f32_16x16x32_bf16 v[114:117], v[184:187], v[192:195], v[114:117]
	v_mfma_f32_16x16x32_bf16 v[102:105], v[176:179], v[200:203], v[102:105]
	v_mfma_f32_16x16x32_bf16 v[98:101], v[184:187], v[200:203], v[98:101]
	v_mfma_f32_16x16x32_bf16 v[86:89], v[176:179], v[208:211], v[86:89]
	v_mfma_f32_16x16x32_bf16 v[82:85], v[184:187], v[208:211], v[82:85]
	v_mfma_f32_16x16x32_bf16 v[70:73], v[176:179], v[216:219], v[70:73]
	v_mfma_f32_16x16x32_bf16 v[66:69], v[184:187], v[216:219], v[66:69]
	s_setprio 0
	s_barrier
	s_add_i32 s34, s59, s41
	v_lshl_add_u64 v[220:221], v[220:221], 0, s[10:11]
	s_mov_b32 m0, s34
	ds_read_b128 v[188:191], v159 offset:49152
	ds_read_b128 v[192:195], v159 offset:50176
	ds_read_b128 v[196:199], v159 offset:51200
	ds_read_b128 v[200:203], v159 offset:52224
	ds_read_b128 v[204:207], v159 offset:53248
	ds_read_b128 v[208:211], v159 offset:54272
	ds_read_b128 v[212:215], v159 offset:55296
	ds_read_b128 v[216:219], v159 offset:56320
	global_load_lds_dwordx4 v[220:221], off
	s_add_i32 m0, s34, 0x2000
	s_add_u32 s30, s30, 0x40080
	v_lshl_add_u64 v[220:221], v[222:223], 0, s[10:11]
	s_addc_u32 s31, s31, 0
	s_add_i32 s34, s60, s41
	global_load_lds_dwordx4 v[220:221], off
	v_lshl_add_u64 v[220:221], s[30:31], 0, v[132:133]
	s_mov_b32 m0, s34
	s_nop 0
	global_load_lds_dwordx4 v[220:221], off
	s_waitcnt vmcnt(5)
	s_waitcnt lgkmcnt(0)
	s_barrier
	s_setprio 1
	s_waitcnt lgkmcnt(0)
	v_mfma_f32_16x16x32_bf16 v[62:65], v[150:153], v[188:191], v[62:65]
	v_mfma_f32_16x16x32_bf16 v[58:61], v[164:167], v[188:191], v[58:61]
	v_lshl_add_u64 v[220:221], s[30:31], 0, v[136:137]
	s_add_i32 m0, s34, 0x2000
	s_nop 0
	global_load_lds_dwordx4 v[220:221], off
	v_mfma_f32_16x16x32_bf16 v[46:49], v[150:153], v[196:199], v[46:49]
	v_mfma_f32_16x16x32_bf16 v[42:45], v[164:167], v[196:199], v[42:45]
	v_mfma_f32_16x16x32_bf16 v[30:33], v[150:153], v[204:207], v[30:33]
	v_mfma_f32_16x16x32_bf16 v[26:29], v[164:167], v[204:207], v[26:29]
	v_mfma_f32_16x16x32_bf16 v[14:17], v[150:153], v[212:215], v[14:17]
	v_mfma_f32_16x16x32_bf16 v[10:13], v[164:167], v[212:215], v[10:13]
	v_mfma_f32_16x16x32_bf16 v[62:65], v[160:163], v[192:195], v[62:65]
	v_mfma_f32_16x16x32_bf16 v[58:61], v[168:171], v[192:195], v[58:61]
	v_lshl_add_u64 v[220:221], v[224:225], 0, s[10:11]
	s_mov_b32 m0, s46
	s_nop 0
	global_load_lds_dwordx4 v[220:221], off
	v_mfma_f32_16x16x32_bf16 v[46:49], v[160:163], v[200:203], v[46:49]
	v_mfma_f32_16x16x32_bf16 v[42:45], v[168:171], v[200:203], v[42:45]
	v_mfma_f32_16x16x32_bf16 v[30:33], v[160:163], v[208:211], v[30:33]
	v_mfma_f32_16x16x32_bf16 v[26:29], v[168:171], v[208:211], v[26:29]
	v_mfma_f32_16x16x32_bf16 v[14:17], v[160:163], v[216:219], v[14:17]
	v_mfma_f32_16x16x32_bf16 v[10:13], v[168:171], v[216:219], v[10:13]
	s_setprio 0
	s_setprio 1
	v_mfma_f32_16x16x32_bf16 v[54:57], v[172:175], v[188:191], v[54:57]
	v_mfma_f32_16x16x32_bf16 v[50:53], v[180:183], v[188:191], v[50:53]
	v_lshl_add_u64 v[220:221], v[226:227], 0, s[10:11]
	s_mov_b32 m0, s47
	s_nop 0
	global_load_lds_dwordx4 v[220:221], off
	v_mfma_f32_16x16x32_bf16 v[38:41], v[172:175], v[196:199], v[38:41]
	v_mfma_f32_16x16x32_bf16 v[34:37], v[180:183], v[196:199], v[34:37]
	v_mfma_f32_16x16x32_bf16 v[22:25], v[172:175], v[204:207], v[22:25]
	v_mfma_f32_16x16x32_bf16 v[18:21], v[180:183], v[204:207], v[18:21]
	v_mfma_f32_16x16x32_bf16 v[6:9], v[172:175], v[212:215], v[6:9]
	v_mfma_f32_16x16x32_bf16 v[2:5], v[180:183], v[212:215], v[2:5]
	v_mfma_f32_16x16x32_bf16 v[54:57], v[176:179], v[192:195], v[54:57]
	v_mfma_f32_16x16x32_bf16 v[50:53], v[184:187], v[192:195], v[50:53]
	v_mfma_f32_16x16x32_bf16 v[38:41], v[176:179], v[200:203], v[38:41]
	v_mfma_f32_16x16x32_bf16 v[34:37], v[184:187], v[200:203], v[34:37]
	v_mfma_f32_16x16x32_bf16 v[22:25], v[176:179], v[208:211], v[22:25]
	v_mfma_f32_16x16x32_bf16 v[18:21], v[184:187], v[208:211], v[18:21]
	v_mfma_f32_16x16x32_bf16 v[6:9], v[176:179], v[216:219], v[6:9]
	v_mfma_f32_16x16x32_bf16 v[2:5], v[184:187], v[216:219], v[2:5]
	s_setprio 0
	s_barrier
	s_add_i32 s58, s58, 2
	s_add_u32 s28, s28, 0x100
	s_addc_u32 s29, s29, 0
	s_cmp_gt_u32 s58, 13
	s_cbranch_scc0 .LBB0_915
	s_and_b64 vcc, exec, s[12:13]
	s_cbranch_vccz .LBB0_918
	s_barrier

.Lwe_6:
	s_waitcnt lgkmcnt(0)
	s_barrier
	s_setprio 1
	s_waitcnt lgkmcnt(0)
	v_mfma_f32_16x16x32_bf16 v[126:129], v[156:159], v[188:191], v[126:129]
	v_mfma_f32_16x16x32_bf16 v[122:125], v[164:167], v[188:191], v[122:125]
	v_mfma_f32_16x16x32_bf16 v[118:121], v[156:159], v[196:199], v[118:121]
	v_mfma_f32_16x16x32_bf16 v[110:113], v[164:167], v[196:199], v[110:113]
	v_mfma_f32_16x16x32_bf16 v[102:105], v[156:159], v[204:207], v[102:105]
	v_mfma_f32_16x16x32_bf16 v[94:97], v[164:167], v[204:207], v[94:97]
	v_mfma_f32_16x16x32_bf16 v[86:89], v[156:159], v[212:215], v[86:89]
	v_mfma_f32_16x16x32_bf16 v[78:81], v[164:167], v[212:215], v[78:81]
	v_mfma_f32_16x16x32_bf16 v[126:129], v[160:163], v[192:195], v[126:129]
	v_mfma_f32_16x16x32_bf16 v[122:125], v[168:171], v[192:195], v[122:125]
	v_mfma_f32_16x16x32_bf16 v[118:121], v[160:163], v[200:203], v[118:121]
	v_mfma_f32_16x16x32_bf16 v[110:113], v[168:171], v[200:203], v[110:113]
	v_mfma_f32_16x16x32_bf16 v[102:105], v[160:163], v[208:211], v[102:105]
	v_mfma_f32_16x16x32_bf16 v[94:97], v[168:171], v[208:211], v[94:97]
	v_mfma_f32_16x16x32_bf16 v[86:89], v[160:163], v[216:219], v[86:89]
	v_mfma_f32_16x16x32_bf16 v[78:81], v[168:171], v[216:219], v[78:81]
	s_setprio 0
	s_setprio 1
	v_mfma_f32_16x16x32_bf16 v[114:117], v[172:175], v[188:191], v[114:117]
	v_mfma_f32_16x16x32_bf16 v[106:109], v[180:183], v[188:191], v[106:109]
	v_mfma_f32_16x16x32_bf16 v[98:101], v[172:175], v[196:199], v[98:101]
	v_mfma_f32_16x16x32_bf16 v[90:93], v[180:183], v[196:199], v[90:93]
	v_mfma_f32_16x16x32_bf16 v[82:85], v[172:175], v[204:207], v[82:85]
	v_mfma_f32_16x16x32_bf16 v[74:77], v[180:183], v[204:207], v[74:77]
	v_mfma_f32_16x16x32_bf16 v[70:73], v[172:175], v[212:215], v[70:73]
	v_mfma_f32_16x16x32_bf16 v[66:69], v[180:183], v[212:215], v[66:69]
	v_mfma_f32_16x16x32_bf16 v[114:117], v[176:179], v[192:195], v[114:117]
	v_mfma_f32_16x16x32_bf16 v[106:109], v[184:187], v[192:195], v[106:109]
	v_mfma_f32_16x16x32_bf16 v[98:101], v[176:179], v[200:203], v[98:101]
	v_mfma_f32_16x16x32_bf16 v[90:93], v[184:187], v[200:203], v[90:93]
	v_mfma_f32_16x16x32_bf16 v[82:85], v[176:179], v[208:211], v[82:85]
	v_mfma_f32_16x16x32_bf16 v[74:77], v[184:187], v[208:211], v[74:77]
	v_mfma_f32_16x16x32_bf16 v[70:73], v[176:179], v[216:219], v[70:73]
	v_mfma_f32_16x16x32_bf16 v[66:69], v[184:187], v[216:219], v[66:69]
	s_setprio 0
	s_barrier
	s_add_i32 s66, s53, s45
	v_lshl_add_u64 v[220:221], s[36:37], 0, v[132:133]
	s_mov_b32 m0, s66
	ds_read_b128 v[188:191], v155 offset:16384
	ds_read_b128 v[192:195], v155 offset:17408
	ds_read_b128 v[196:199], v155 offset:18432
	ds_read_b128 v[200:203], v155 offset:19456
	ds_read_b128 v[204:207], v155 offset:20480
	ds_read_b128 v[208:211], v155 offset:21504
	ds_read_b128 v[212:215], v155 offset:22528
	ds_read_b128 v[216:219], v155 offset:23552
	global_load_lds_dwordx4 v[220:221], off
	s_add_i32 m0, s66, 0x2000
	s_add_u32 s66, s36, 0x80000
	v_lshl_add_u64 v[222:223], s[36:37], 0, v[136:137]
	s_addc_u32 s67, s37, 0
	s_add_i32 s69, s54, s45
	global_load_lds_dwordx4 v[222:223], off
	v_lshl_add_u64 v[224:225], s[66:67], 0, v[132:133]
	s_mov_b32 m0, s69
	v_lshl_add_u64 v[226:227], s[38:39], 0, v[134:135]
	global_load_lds_dwordx4 v[224:225], off
	s_cmp_eq_u32 s68, 0
	s_cbranch_scc1 .Lw8_7
	s_waitcnt vmcnt(21)
	s_branch .Lwe_7

.Lwe_7:
	s_waitcnt lgkmcnt(0)
	s_barrier
	s_setprio 1
	s_waitcnt lgkmcnt(0)
	v_mfma_f32_16x16x32_bf16 v[62:65], v[156:159], v[188:191], v[62:65]
	v_mfma_f32_16x16x32_bf16 v[58:61], v[164:167], v[188:191], v[58:61]
	v_lshl_add_u64 v[224:225], s[66:67], 0, v[136:137]
	s_add_i32 m0, s69, 0x2000
	s_nop 0
	global_load_lds_dwordx4 v[224:225], off
	v_mfma_f32_16x16x32_bf16 v[54:57], v[156:159], v[196:199], v[54:57]
	v_mfma_f32_16x16x32_bf16 v[46:49], v[164:167], v[196:199], v[46:49]
	v_mfma_f32_16x16x32_bf16 v[38:41], v[156:159], v[204:207], v[38:41]
	v_mfma_f32_16x16x32_bf16 v[30:33], v[164:167], v[204:207], v[30:33]
	v_mfma_f32_16x16x32_bf16 v[22:25], v[156:159], v[212:215], v[22:25]
	v_mfma_f32_16x16x32_bf16 v[14:17], v[164:167], v[212:215], v[14:17]
	v_mfma_f32_16x16x32_bf16 v[62:65], v[160:163], v[192:195], v[62:65]
	v_mfma_f32_16x16x32_bf16 v[58:61], v[168:171], v[192:195], v[58:61]
	v_lshl_add_u64 v[224:225], s[38:39], 0, v[130:131]
	s_mov_b32 m0, s27
	s_nop 0
	global_load_lds_dwordx4 v[224:225], off
	v_mfma_f32_16x16x32_bf16 v[54:57], v[160:163], v[200:203], v[54:57]
	v_mfma_f32_16x16x32_bf16 v[46:49], v[168:171], v[200:203], v[46:49]
	v_mfma_f32_16x16x32_bf16 v[38:41], v[160:163], v[208:211], v[38:41]
	v_mfma_f32_16x16x32_bf16 v[30:33], v[168:171], v[208:211], v[30:33]
	v_mfma_f32_16x16x32_bf16 v[22:25], v[160:163], v[216:219], v[22:25]
	v_mfma_f32_16x16x32_bf16 v[14:17], v[168:171], v[216:219], v[14:17]
	s_setprio 0
	s_setprio 1
	v_mfma_f32_16x16x32_bf16 v[50:53], v[172:175], v[188:191], v[50:53]
	v_mfma_f32_16x16x32_bf16 v[42:45], v[180:183], v[188:191], v[42:45]
	s_mov_b32 m0, s46
	s_nop 0
	global_load_lds_dwordx4 v[226:227], off
	v_mfma_f32_16x16x32_bf16 v[34:37], v[172:175], v[196:199], v[34:37]
	v_mfma_f32_16x16x32_bf16 v[26:29], v[180:183], v[196:199], v[26:29]
	v_mfma_f32_16x16x32_bf16 v[18:21], v[172:175], v[204:207], v[18:21]
	v_mfma_f32_16x16x32_bf16 v[10:13], v[180:183], v[204:207], v[10:13]
	v_mfma_f32_16x16x32_bf16 v[6:9], v[172:175], v[212:215], v[6:9]
	v_mfma_f32_16x16x32_bf16 v[2:5], v[180:183], v[212:215], v[2:5]
	v_mfma_f32_16x16x32_bf16 v[50:53], v[176:179], v[192:195], v[50:53]
	v_mfma_f32_16x16x32_bf16 v[42:45], v[184:187], v[192:195], v[42:45]
	v_mfma_f32_16x16x32_bf16 v[34:37], v[176:179], v[200:203], v[34:37]
	v_mfma_f32_16x16x32_bf16 v[26:29], v[184:187], v[200:203], v[26:29]
	v_mfma_f32_16x16x32_bf16 v[18:21], v[176:179], v[208:211], v[18:21]
	v_mfma_f32_16x16x32_bf16 v[10:13], v[184:187], v[208:211], v[10:13]
	v_mfma_f32_16x16x32_bf16 v[6:9], v[176:179], v[216:219], v[6:9]
	v_mfma_f32_16x16x32_bf16 v[2:5], v[184:187], v[216:219], v[2:5]
	s_setprio 0
	s_barrier
	s_add_i32 s66, 0, 0x18000
	s_add_i32 s67, 0, 0x1c000
	v_add_u32_e32 v168, s66, v150
	v_add_u32_e32 v184, s67, v150
	ds_read_b128 v[156:159], v168
	ds_read_b128 v[160:163], v168 offset:1024
	ds_read_b128 v[164:167], v168 offset:2048
	ds_read_b128 v[168:171], v168 offset:3072
	ds_read_b128 v[172:175], v184
	ds_read_b128 v[176:179], v184 offset:1024
	ds_read_b128 v[180:183], v184 offset:2048
	ds_read_b128 v[184:187], v184 offset:3072
	s_add_u32 s38, s38, 0x80000
	s_addc_u32 s39, s39, 0
	s_mov_b32 m0, s47
	v_lshl_add_u64 v[228:229], s[38:39], 0, v[130:131]
	ds_read_b128 v[188:191], v155 offset:32768
	ds_read_b128 v[192:195], v155 offset:33792
	ds_read_b128 v[196:199], v155 offset:34816
	ds_read_b128 v[200:203], v155 offset:35840
	ds_read_b128 v[204:207], v155 offset:36864
	ds_read_b128 v[208:211], v155 offset:37888
	ds_read_b128 v[212:215], v155 offset:38912
	ds_read_b128 v[216:219], v155 offset:39936
	global_load_lds_dwordx4 v[228:229], off
	v_lshl_add_u64 v[228:229], s[38:39], 0, v[134:135]
	s_mov_b32 m0, s48
	s_nop 0
	global_load_lds_dwordx4 v[228:229], off
	s_waitcnt vmcnt(8)
	s_waitcnt lgkmcnt(0)
	s_barrier
	s_setprio 1
	s_waitcnt lgkmcnt(0)
	v_mfma_f32_16x16x32_bf16 v[126:129], v[156:159], v[188:191], v[126:129]
	v_mfma_f32_16x16x32_bf16 v[122:125], v[164:167], v[188:191], v[122:125]
	v_mfma_f32_16x16x32_bf16 v[118:121], v[156:159], v[196:199], v[118:121]
	v_mfma_f32_16x16x32_bf16 v[110:113], v[164:167], v[196:199], v[110:113]
	v_mfma_f32_16x16x32_bf16 v[102:105], v[156:159], v[204:207], v[102:105]
	v_mfma_f32_16x16x32_bf16 v[94:97], v[164:167], v[204:207], v[94:97]
	v_mfma_f32_16x16x32_bf16 v[86:89], v[156:159], v[212:215], v[86:89]
	v_mfma_f32_16x16x32_bf16 v[78:81], v[164:167], v[212:215], v[78:81]
	v_mfma_f32_16x16x32_bf16 v[126:129], v[160:163], v[192:195], v[126:129]
	v_mfma_f32_16x16x32_bf16 v[122:125], v[168:171], v[192:195], v[122:125]
	v_mfma_f32_16x16x32_bf16 v[118:121], v[160:163], v[200:203], v[118:121]
	v_mfma_f32_16x16x32_bf16 v[110:113], v[168:171], v[200:203], v[110:113]
	v_mfma_f32_16x16x32_bf16 v[102:105], v[160:163], v[208:211], v[102:105]
	v_mfma_f32_16x16x32_bf16 v[94:97], v[168:171], v[208:211], v[94:97]
	v_mfma_f32_16x16x32_bf16 v[86:89], v[160:163], v[216:219], v[86:89]
	v_mfma_f32_16x16x32_bf16 v[78:81], v[168:171], v[216:219], v[78:81]
	s_setprio 0
	s_setprio 1
	v_mfma_f32_16x16x32_bf16 v[114:117], v[172:175], v[188:191], v[114:117]
	v_mfma_f32_16x16x32_bf16 v[106:109], v[180:183], v[188:191], v[106:109]
	v_mfma_f32_16x16x32_bf16 v[98:101], v[172:175], v[196:199], v[98:101]
	v_mfma_f32_16x16x32_bf16 v[90:93], v[180:183], v[196:199], v[90:93]
	v_mfma_f32_16x16x32_bf16 v[82:85], v[172:175], v[204:207], v[82:85]
	v_mfma_f32_16x16x32_bf16 v[74:77], v[180:183], v[204:207], v[74:77]
	v_mfma_f32_16x16x32_bf16 v[70:73], v[172:175], v[212:215], v[70:73]
	v_mfma_f32_16x16x32_bf16 v[66:69], v[180:183], v[212:215], v[66:69]
	v_mfma_f32_16x16x32_bf16 v[114:117], v[176:179], v[192:195], v[114:117]
	v_mfma_f32_16x16x32_bf16 v[106:109], v[184:187], v[192:195], v[106:109]
	v_mfma_f32_16x16x32_bf16 v[98:101], v[176:179], v[200:203], v[98:101]
	v_mfma_f32_16x16x32_bf16 v[90:93], v[184:187], v[200:203], v[90:93]
	v_mfma_f32_16x16x32_bf16 v[82:85], v[176:179], v[208:211], v[82:85]
	v_mfma_f32_16x16x32_bf16 v[74:77], v[184:187], v[208:211], v[74:77]
	v_mfma_f32_16x16x32_bf16 v[70:73], v[176:179], v[216:219], v[70:73]
	v_mfma_f32_16x16x32_bf16 v[66:69], v[184:187], v[216:219], v[66:69]
	s_setprio 0
	s_barrier
	s_add_i32 s38, s66, s45
	v_lshl_add_u64 v[220:221], v[220:221], 0, s[8:9]
	s_mov_b32 m0, s38
	ds_read_b128 v[188:191], v155 offset:49152
	ds_read_b128 v[192:195], v155 offset:50176
	ds_read_b128 v[196:199], v155 offset:51200
	ds_read_b128 v[200:203], v155 offset:52224
	ds_read_b128 v[204:207], v155 offset:53248
	ds_read_b128 v[208:211], v155 offset:54272
	ds_read_b128 v[212:215], v155 offset:55296
	ds_read_b128 v[216:219], v155 offset:56320
	global_load_lds_dwordx4 v[220:221], off
	s_add_i32 m0, s38, 0x2000
	s_add_u32 s36, s36, 0x80080
	v_lshl_add_u64 v[220:221], v[222:223], 0, s[8:9]
	s_addc_u32 s37, s37, 0
	s_add_i32 s38, s67, s45
	global_load_lds_dwordx4 v[220:221], off
	v_lshl_add_u64 v[220:221], s[36:37], 0, v[132:133]
	s_mov_b32 m0, s38
	s_nop 0
	global_load_lds_dwordx4 v[220:221], off
	s_waitcnt vmcnt(5)
	s_waitcnt lgkmcnt(0)
	s_barrier
	s_setprio 1
	s_waitcnt lgkmcnt(0)
	v_mfma_f32_16x16x32_bf16 v[62:65], v[156:159], v[188:191], v[62:65]
	v_mfma_f32_16x16x32_bf16 v[58:61], v[164:167], v[188:191], v[58:61]
	v_lshl_add_u64 v[220:221], s[36:37], 0, v[136:137]
	s_add_i32 m0, s38, 0x2000
	s_nop 0
	global_load_lds_dwordx4 v[220:221], off
	v_mfma_f32_16x16x32_bf16 v[54:57], v[156:159], v[196:199], v[54:57]
	v_mfma_f32_16x16x32_bf16 v[46:49], v[164:167], v[196:199], v[46:49]
	v_mfma_f32_16x16x32_bf16 v[38:41], v[156:159], v[204:207], v[38:41]
	v_mfma_f32_16x16x32_bf16 v[30:33], v[164:167], v[204:207], v[30:33]
	v_mfma_f32_16x16x32_bf16 v[22:25], v[156:159], v[212:215], v[22:25]
	v_mfma_f32_16x16x32_bf16 v[14:17], v[164:167], v[212:215], v[14:17]
	v_mfma_f32_16x16x32_bf16 v[62:65], v[160:163], v[192:195], v[62:65]
	v_mfma_f32_16x16x32_bf16 v[58:61], v[168:171], v[192:195], v[58:61]
	v_lshl_add_u64 v[220:221], v[224:225], 0, s[8:9]
	s_mov_b32 m0, s49
	s_nop 0
	global_load_lds_dwordx4 v[220:221], off
	v_mfma_f32_16x16x32_bf16 v[54:57], v[160:163], v[200:203], v[54:57]
	v_mfma_f32_16x16x32_bf16 v[46:49], v[168:171], v[200:203], v[46:49]
	v_mfma_f32_16x16x32_bf16 v[38:41], v[160:163], v[208:211], v[38:41]
	v_mfma_f32_16x16x32_bf16 v[30:33], v[168:171], v[208:211], v[30:33]
	v_mfma_f32_16x16x32_bf16 v[22:25], v[160:163], v[216:219], v[22:25]
	v_mfma_f32_16x16x32_bf16 v[14:17], v[168:171], v[216:219], v[14:17]
	s_setprio 0
	s_setprio 1
	v_mfma_f32_16x16x32_bf16 v[50:53], v[172:175], v[188:191], v[50:53]
	v_mfma_f32_16x16x32_bf16 v[42:45], v[180:183], v[188:191], v[42:45]
	v_lshl_add_u64 v[220:221], v[226:227], 0, s[8:9]
	s_mov_b32 m0, s50
	s_nop 0
	global_load_lds_dwordx4 v[220:221], off
	v_mfma_f32_16x16x32_bf16 v[34:37], v[172:175], v[196:199], v[34:37]
	v_mfma_f32_16x16x32_bf16 v[26:29], v[180:183], v[196:199], v[26:29]
	v_mfma_f32_16x16x32_bf16 v[18:21], v[172:175], v[204:207], v[18:21]
	v_mfma_f32_16x16x32_bf16 v[10:13], v[180:183], v[204:207], v[10:13]
	v_mfma_f32_16x16x32_bf16 v[6:9], v[172:175], v[212:215], v[6:9]
	v_mfma_f32_16x16x32_bf16 v[2:5], v[180:183], v[212:215], v[2:5]
	v_mfma_f32_16x16x32_bf16 v[50:53], v[176:179], v[192:195], v[50:53]
	v_mfma_f32_16x16x32_bf16 v[42:45], v[184:187], v[192:195], v[42:45]
	v_mfma_f32_16x16x32_bf16 v[34:37], v[176:179], v[200:203], v[34:37]
	v_mfma_f32_16x16x32_bf16 v[26:29], v[184:187], v[200:203], v[26:29]
	v_mfma_f32_16x16x32_bf16 v[18:21], v[176:179], v[208:211], v[18:21]
	v_mfma_f32_16x16x32_bf16 v[10:13], v[184:187], v[208:211], v[10:13]
	v_mfma_f32_16x16x32_bf16 v[6:9], v[176:179], v[216:219], v[6:9]
	v_mfma_f32_16x16x32_bf16 v[2:5], v[184:187], v[216:219], v[2:5]
	s_setprio 0
	s_barrier
	s_add_i32 s65, s65, 2
	s_add_u32 s34, s34, 0x100
	s_addc_u32 s35, s35, 0
	s_cmp_gt_u32 s65, 29
	s_cbranch_scc0 .LBB0_1009
	s_and_b64 vcc, exec, s[10:11]
	s_cbranch_vccz .LBB0_1012
	s_barrier

.Lwe_8:
	s_waitcnt lgkmcnt(0)
	s_barrier
	s_setprio 1
	s_waitcnt lgkmcnt(0)
	v_mfma_f32_16x16x32_bf16 v[126:129], v[156:159], v[188:191], v[126:129]
	v_mfma_f32_16x16x32_bf16 v[122:125], v[164:167], v[188:191], v[122:125]
	v_mfma_f32_16x16x32_bf16 v[118:121], v[156:159], v[196:199], v[118:121]
	v_mfma_f32_16x16x32_bf16 v[110:113], v[164:167], v[196:199], v[110:113]
	v_mfma_f32_16x16x32_bf16 v[102:105], v[156:159], v[204:207], v[102:105]
	v_mfma_f32_16x16x32_bf16 v[94:97], v[164:167], v[204:207], v[94:97]
	v_mfma_f32_16x16x32_bf16 v[86:89], v[156:159], v[212:215], v[86:89]
	v_mfma_f32_16x16x32_bf16 v[78:81], v[164:167], v[212:215], v[78:81]
	v_mfma_f32_16x16x32_bf16 v[126:129], v[160:163], v[192:195], v[126:129]
	v_mfma_f32_16x16x32_bf16 v[122:125], v[168:171], v[192:195], v[122:125]
	v_mfma_f32_16x16x32_bf16 v[118:121], v[160:163], v[200:203], v[118:121]
	v_mfma_f32_16x16x32_bf16 v[110:113], v[168:171], v[200:203], v[110:113]
	v_mfma_f32_16x16x32_bf16 v[102:105], v[160:163], v[208:211], v[102:105]
	v_mfma_f32_16x16x32_bf16 v[94:97], v[168:171], v[208:211], v[94:97]
	v_mfma_f32_16x16x32_bf16 v[86:89], v[160:163], v[216:219], v[86:89]
	v_mfma_f32_16x16x32_bf16 v[78:81], v[168:171], v[216:219], v[78:81]
	s_setprio 0
	s_setprio 1
	v_mfma_f32_16x16x32_bf16 v[114:117], v[172:175], v[188:191], v[114:117]
	v_mfma_f32_16x16x32_bf16 v[106:109], v[180:183], v[188:191], v[106:109]
	v_mfma_f32_16x16x32_bf16 v[98:101], v[172:175], v[196:199], v[98:101]
	v_mfma_f32_16x16x32_bf16 v[90:93], v[180:183], v[196:199], v[90:93]
	v_mfma_f32_16x16x32_bf16 v[82:85], v[172:175], v[204:207], v[82:85]
	v_mfma_f32_16x16x32_bf16 v[74:77], v[180:183], v[204:207], v[74:77]
	v_mfma_f32_16x16x32_bf16 v[70:73], v[172:175], v[212:215], v[70:73]
	v_mfma_f32_16x16x32_bf16 v[66:69], v[180:183], v[212:215], v[66:69]
	v_mfma_f32_16x16x32_bf16 v[114:117], v[176:179], v[192:195], v[114:117]
	v_mfma_f32_16x16x32_bf16 v[106:109], v[184:187], v[192:195], v[106:109]
	v_mfma_f32_16x16x32_bf16 v[98:101], v[176:179], v[200:203], v[98:101]
	v_mfma_f32_16x16x32_bf16 v[90:93], v[184:187], v[200:203], v[90:93]
	v_mfma_f32_16x16x32_bf16 v[82:85], v[176:179], v[208:211], v[82:85]
	v_mfma_f32_16x16x32_bf16 v[74:77], v[184:187], v[208:211], v[74:77]
	v_mfma_f32_16x16x32_bf16 v[70:73], v[176:179], v[216:219], v[70:73]
	v_mfma_f32_16x16x32_bf16 v[66:69], v[184:187], v[216:219], v[66:69]
	s_setprio 0
	s_barrier
	s_add_i32 s56, s46, s36
	v_lshl_add_u64 v[220:221], s[26:27], 0, v[134:135]
	s_mov_b32 m0, s56
	ds_read_b128 v[188:191], v155 offset:16384
	ds_read_b128 v[192:195], v155 offset:17408
	ds_read_b128 v[196:199], v155 offset:18432
	ds_read_b128 v[200:203], v155 offset:19456
	ds_read_b128 v[204:207], v155 offset:20480
	ds_read_b128 v[208:211], v155 offset:21504
	ds_read_b128 v[212:215], v155 offset:22528
	ds_read_b128 v[216:219], v155 offset:23552
	global_load_lds_dwordx4 v[220:221], off
	s_add_i32 m0, s56, 0x2000
	s_add_u32 s56, s26, 0x80000
	v_lshl_add_u64 v[222:223], s[26:27], 0, v[130:131]
	s_addc_u32 s57, s27, 0
	s_add_i32 s59, s47, s36
	global_load_lds_dwordx4 v[222:223], off
	v_lshl_add_u64 v[224:225], s[56:57], 0, v[134:135]
	s_mov_b32 m0, s59
	v_lshl_add_u64 v[226:227], s[28:29], 0, v[132:133]
	global_load_lds_dwordx4 v[224:225], off
	s_cmp_eq_u32 s58, 0
	s_cbranch_scc1 .Lw8_9
	s_waitcnt vmcnt(21)
	s_branch .Lwe_9

.Lwe_9:
	s_waitcnt lgkmcnt(0)
	s_barrier
	s_setprio 1
	s_waitcnt lgkmcnt(0)
	v_mfma_f32_16x16x32_bf16 v[62:65], v[156:159], v[188:191], v[62:65]
	v_mfma_f32_16x16x32_bf16 v[58:61], v[164:167], v[188:191], v[58:61]
	v_lshl_add_u64 v[224:225], s[56:57], 0, v[130:131]
	s_add_i32 m0, s59, 0x2000
	s_nop 0
	global_load_lds_dwordx4 v[224:225], off
	v_mfma_f32_16x16x32_bf16 v[54:57], v[156:159], v[196:199], v[54:57]
	v_mfma_f32_16x16x32_bf16 v[46:49], v[164:167], v[196:199], v[46:49]
	v_mfma_f32_16x16x32_bf16 v[38:41], v[156:159], v[204:207], v[38:41]
	v_mfma_f32_16x16x32_bf16 v[30:33], v[164:167], v[204:207], v[30:33]
	v_mfma_f32_16x16x32_bf16 v[22:25], v[156:159], v[212:215], v[22:25]
	v_mfma_f32_16x16x32_bf16 v[14:17], v[164:167], v[212:215], v[14:17]
	v_mfma_f32_16x16x32_bf16 v[62:65], v[160:163], v[192:195], v[62:65]
	v_mfma_f32_16x16x32_bf16 v[58:61], v[168:171], v[192:195], v[58:61]
	v_lshl_add_u64 v[224:225], s[28:29], 0, v[136:137]
	s_mov_b32 m0, s19
	s_nop 0
	global_load_lds_dwordx4 v[224:225], off
	v_mfma_f32_16x16x32_bf16 v[54:57], v[160:163], v[200:203], v[54:57]
	v_mfma_f32_16x16x32_bf16 v[46:49], v[168:171], v[200:203], v[46:49]
	v_mfma_f32_16x16x32_bf16 v[38:41], v[160:163], v[208:211], v[38:41]
	v_mfma_f32_16x16x32_bf16 v[30:33], v[168:171], v[208:211], v[30:33]
	v_mfma_f32_16x16x32_bf16 v[22:25], v[160:163], v[216:219], v[22:25]
	v_mfma_f32_16x16x32_bf16 v[14:17], v[168:171], v[216:219], v[14:17]
	s_setprio 0
	s_setprio 1
	v_mfma_f32_16x16x32_bf16 v[50:53], v[172:175], v[188:191], v[50:53]
	v_mfma_f32_16x16x32_bf16 v[42:45], v[180:183], v[188:191], v[42:45]
	s_mov_b32 m0, s39
	s_nop 0
	global_load_lds_dwordx4 v[226:227], off
	v_mfma_f32_16x16x32_bf16 v[34:37], v[172:175], v[196:199], v[34:37]
	v_mfma_f32_16x16x32_bf16 v[26:29], v[180:183], v[196:199], v[26:29]
	v_mfma_f32_16x16x32_bf16 v[18:21], v[172:175], v[204:207], v[18:21]
	v_mfma_f32_16x16x32_bf16 v[10:13], v[180:183], v[204:207], v[10:13]
	v_mfma_f32_16x16x32_bf16 v[6:9], v[172:175], v[212:215], v[6:9]
	v_mfma_f32_16x16x32_bf16 v[2:5], v[180:183], v[212:215], v[2:5]
	v_mfma_f32_16x16x32_bf16 v[50:53], v[176:179], v[192:195], v[50:53]
	v_mfma_f32_16x16x32_bf16 v[42:45], v[184:187], v[192:195], v[42:45]
	v_mfma_f32_16x16x32_bf16 v[34:37], v[176:179], v[200:203], v[34:37]
	v_mfma_f32_16x16x32_bf16 v[26:29], v[184:187], v[200:203], v[26:29]
	v_mfma_f32_16x16x32_bf16 v[18:21], v[176:179], v[208:211], v[18:21]
	v_mfma_f32_16x16x32_bf16 v[10:13], v[184:187], v[208:211], v[10:13]
	v_mfma_f32_16x16x32_bf16 v[6:9], v[176:179], v[216:219], v[6:9]
	v_mfma_f32_16x16x32_bf16 v[2:5], v[184:187], v[216:219], v[2:5]
	s_setprio 0
	s_barrier
	s_add_i32 s56, 0, 0x18000
	s_add_i32 s57, 0, 0x1c000
	v_add_u32_e32 v168, s56, v150
	v_add_u32_e32 v184, s57, v150
	ds_read_b128 v[156:159], v168
	ds_read_b128 v[160:163], v168 offset:1024
	ds_read_b128 v[164:167], v168 offset:2048
	ds_read_b128 v[168:171], v168 offset:3072
	ds_read_b128 v[172:175], v184
	ds_read_b128 v[176:179], v184 offset:1024
	ds_read_b128 v[180:183], v184 offset:2048
	ds_read_b128 v[184:187], v184 offset:3072
	s_add_u32 s28, s28, 0x80000
	s_addc_u32 s29, s29, 0
	s_mov_b32 m0, s40
	v_lshl_add_u64 v[228:229], s[28:29], 0, v[136:137]
	ds_read_b128 v[188:191], v155 offset:32768
	ds_read_b128 v[192:195], v155 offset:33792
	ds_read_b128 v[196:199], v155 offset:34816
	ds_read_b128 v[200:203], v155 offset:35840
	ds_read_b128 v[204:207], v155 offset:36864
	ds_read_b128 v[208:211], v155 offset:37888
	ds_read_b128 v[212:215], v155 offset:38912
	ds_read_b128 v[216:219], v155 offset:39936
	global_load_lds_dwordx4 v[228:229], off
	v_lshl_add_u64 v[228:229], s[28:29], 0, v[132:133]
	s_mov_b32 m0, s41
	s_nop 0
	global_load_lds_dwordx4 v[228:229], off
	s_waitcnt vmcnt(8)
	s_waitcnt lgkmcnt(0)
	s_barrier
	s_setprio 1
	s_waitcnt lgkmcnt(0)
	v_mfma_f32_16x16x32_bf16 v[126:129], v[156:159], v[188:191], v[126:129]
	v_mfma_f32_16x16x32_bf16 v[122:125], v[164:167], v[188:191], v[122:125]
	v_mfma_f32_16x16x32_bf16 v[118:121], v[156:159], v[196:199], v[118:121]
	v_mfma_f32_16x16x32_bf16 v[110:113], v[164:167], v[196:199], v[110:113]
	v_mfma_f32_16x16x32_bf16 v[102:105], v[156:159], v[204:207], v[102:105]
	v_mfma_f32_16x16x32_bf16 v[94:97], v[164:167], v[204:207], v[94:97]
	v_mfma_f32_16x16x32_bf16 v[86:89], v[156:159], v[212:215], v[86:89]
	v_mfma_f32_16x16x32_bf16 v[78:81], v[164:167], v[212:215], v[78:81]
	v_mfma_f32_16x16x32_bf16 v[126:129], v[160:163], v[192:195], v[126:129]
	v_mfma_f32_16x16x32_bf16 v[122:125], v[168:171], v[192:195], v[122:125]
	v_mfma_f32_16x16x32_bf16 v[118:121], v[160:163], v[200:203], v[118:121]
	v_mfma_f32_16x16x32_bf16 v[110:113], v[168:171], v[200:203], v[110:113]
	v_mfma_f32_16x16x32_bf16 v[102:105], v[160:163], v[208:211], v[102:105]
	v_mfma_f32_16x16x32_bf16 v[94:97], v[168:171], v[208:211], v[94:97]
	v_mfma_f32_16x16x32_bf16 v[86:89], v[160:163], v[216:219], v[86:89]
	v_mfma_f32_16x16x32_bf16 v[78:81], v[168:171], v[216:219], v[78:81]
	s_setprio 0
	s_setprio 1
	v_mfma_f32_16x16x32_bf16 v[114:117], v[172:175], v[188:191], v[114:117]
	v_mfma_f32_16x16x32_bf16 v[106:109], v[180:183], v[188:191], v[106:109]
	v_mfma_f32_16x16x32_bf16 v[98:101], v[172:175], v[196:199], v[98:101]
	v_mfma_f32_16x16x32_bf16 v[90:93], v[180:183], v[196:199], v[90:93]
	v_mfma_f32_16x16x32_bf16 v[82:85], v[172:175], v[204:207], v[82:85]
	v_mfma_f32_16x16x32_bf16 v[74:77], v[180:183], v[204:207], v[74:77]
	v_mfma_f32_16x16x32_bf16 v[70:73], v[172:175], v[212:215], v[70:73]
	v_mfma_f32_16x16x32_bf16 v[66:69], v[180:183], v[212:215], v[66:69]
	v_mfma_f32_16x16x32_bf16 v[114:117], v[176:179], v[192:195], v[114:117]
	v_mfma_f32_16x16x32_bf16 v[106:109], v[184:187], v[192:195], v[106:109]
	v_mfma_f32_16x16x32_bf16 v[98:101], v[176:179], v[200:203], v[98:101]
	v_mfma_f32_16x16x32_bf16 v[90:93], v[184:187], v[200:203], v[90:93]
	v_mfma_f32_16x16x32_bf16 v[82:85], v[176:179], v[208:211], v[82:85]
	v_mfma_f32_16x16x32_bf16 v[74:77], v[184:187], v[208:211], v[74:77]
	v_mfma_f32_16x16x32_bf16 v[70:73], v[176:179], v[216:219], v[70:73]
	v_mfma_f32_16x16x32_bf16 v[66:69], v[184:187], v[216:219], v[66:69]
	s_setprio 0
	s_barrier
	s_add_i32 s28, s56, s36
	v_lshl_add_u64 v[220:221], v[220:221], 0, s[6:7]
	s_mov_b32 m0, s28
	ds_read_b128 v[188:191], v155 offset:49152
	ds_read_b128 v[192:195], v155 offset:50176
	ds_read_b128 v[196:199], v155 offset:51200
	ds_read_b128 v[200:203], v155 offset:52224
	ds_read_b128 v[204:207], v155 offset:53248
	ds_read_b128 v[208:211], v155 offset:54272
	ds_read_b128 v[212:215], v155 offset:55296
	ds_read_b128 v[216:219], v155 offset:56320
	global_load_lds_dwordx4 v[220:221], off
	s_add_i32 m0, s28, 0x2000
	s_add_u32 s26, s26, 0x80080
	v_lshl_add_u64 v[220:221], v[222:223], 0, s[6:7]
	s_addc_u32 s27, s27, 0
	s_add_i32 s28, s57, s36
	global_load_lds_dwordx4 v[220:221], off
	v_lshl_add_u64 v[220:221], s[26:27], 0, v[134:135]
	s_mov_b32 m0, s28
	s_nop 0
	global_load_lds_dwordx4 v[220:221], off
	s_waitcnt vmcnt(5)
	s_waitcnt lgkmcnt(0)
	s_barrier
	s_setprio 1
	s_waitcnt lgkmcnt(0)
	v_mfma_f32_16x16x32_bf16 v[62:65], v[156:159], v[188:191], v[62:65]
	v_mfma_f32_16x16x32_bf16 v[58:61], v[164:167], v[188:191], v[58:61]
	v_lshl_add_u64 v[220:221], s[26:27], 0, v[130:131]
	s_add_i32 m0, s28, 0x2000
	s_nop 0
	global_load_lds_dwordx4 v[220:221], off
	v_mfma_f32_16x16x32_bf16 v[54:57], v[156:159], v[196:199], v[54:57]
	v_mfma_f32_16x16x32_bf16 v[46:49], v[164:167], v[196:199], v[46:49]
	v_mfma_f32_16x16x32_bf16 v[38:41], v[156:159], v[204:207], v[38:41]
	v_mfma_f32_16x16x32_bf16 v[30:33], v[164:167], v[204:207], v[30:33]
	v_mfma_f32_16x16x32_bf16 v[22:25], v[156:159], v[212:215], v[22:25]
	v_mfma_f32_16x16x32_bf16 v[14:17], v[164:167], v[212:215], v[14:17]
	v_mfma_f32_16x16x32_bf16 v[62:65], v[160:163], v[192:195], v[62:65]
	v_mfma_f32_16x16x32_bf16 v[58:61], v[168:171], v[192:195], v[58:61]
	v_lshl_add_u64 v[220:221], v[224:225], 0, s[6:7]
	s_mov_b32 m0, s42
	s_nop 0
	global_load_lds_dwordx4 v[220:221], off
	v_mfma_f32_16x16x32_bf16 v[54:57], v[160:163], v[200:203], v[54:57]
	v_mfma_f32_16x16x32_bf16 v[46:49], v[168:171], v[200:203], v[46:49]
	v_mfma_f32_16x16x32_bf16 v[38:41], v[160:163], v[208:211], v[38:41]
	v_mfma_f32_16x16x32_bf16 v[30:33], v[168:171], v[208:211], v[30:33]
	v_mfma_f32_16x16x32_bf16 v[22:25], v[160:163], v[216:219], v[22:25]
	v_mfma_f32_16x16x32_bf16 v[14:17], v[168:171], v[216:219], v[14:17]
	s_setprio 0
	s_setprio 1
	v_mfma_f32_16x16x32_bf16 v[50:53], v[172:175], v[188:191], v[50:53]
	v_mfma_f32_16x16x32_bf16 v[42:45], v[180:183], v[188:191], v[42:45]
	v_lshl_add_u64 v[220:221], v[226:227], 0, s[6:7]
	s_mov_b32 m0, s43
	s_nop 0
	global_load_lds_dwordx4 v[220:221], off
	v_mfma_f32_16x16x32_bf16 v[34:37], v[172:175], v[196:199], v[34:37]
	v_mfma_f32_16x16x32_bf16 v[26:29], v[180:183], v[196:199], v[26:29]
	v_mfma_f32_16x16x32_bf16 v[18:21], v[172:175], v[204:207], v[18:21]
	v_mfma_f32_16x16x32_bf16 v[10:13], v[180:183], v[204:207], v[10:13]
	v_mfma_f32_16x16x32_bf16 v[6:9], v[172:175], v[212:215], v[6:9]
	v_mfma_f32_16x16x32_bf16 v[2:5], v[180:183], v[212:215], v[2:5]
	v_mfma_f32_16x16x32_bf16 v[50:53], v[176:179], v[192:195], v[50:53]
	v_mfma_f32_16x16x32_bf16 v[42:45], v[184:187], v[192:195], v[42:45]
	v_mfma_f32_16x16x32_bf16 v[34:37], v[176:179], v[200:203], v[34:37]
	v_mfma_f32_16x16x32_bf16 v[26:29], v[184:187], v[200:203], v[26:29]
	v_mfma_f32_16x16x32_bf16 v[18:21], v[176:179], v[208:211], v[18:21]
	v_mfma_f32_16x16x32_bf16 v[10:13], v[184:187], v[208:211], v[10:13]
	v_mfma_f32_16x16x32_bf16 v[6:9], v[176:179], v[216:219], v[6:9]
	v_mfma_f32_16x16x32_bf16 v[2:5], v[184:187], v[216:219], v[2:5]
	s_setprio 0
	s_barrier
	s_add_i32 s55, s55, 2
	s_add_u32 s24, s24, 0x100
	s_addc_u32 s25, s25, 0
	s_cmp_gt_u32 s55, 29
	s_cbranch_scc0 .LBB0_1173
	s_and_b64 vcc, exec, s[8:9]
	s_cbranch_vccz .LBB0_1176
	s_barrier

.Lwe_10:
	s_waitcnt lgkmcnt(0)
	s_barrier
	s_setprio 1
	s_waitcnt lgkmcnt(0)
	v_mfma_f32_16x16x32_bf16 v[126:129], v[156:159], v[188:191], v[126:129]
	v_mfma_f32_16x16x32_bf16 v[122:125], v[164:167], v[188:191], v[122:125]
	v_mfma_f32_16x16x32_bf16 v[118:121], v[156:159], v[196:199], v[118:121]
	v_mfma_f32_16x16x32_bf16 v[110:113], v[164:167], v[196:199], v[110:113]
	v_mfma_f32_16x16x32_bf16 v[102:105], v[156:159], v[204:207], v[102:105]
	v_mfma_f32_16x16x32_bf16 v[94:97], v[164:167], v[204:207], v[94:97]
	v_mfma_f32_16x16x32_bf16 v[86:89], v[156:159], v[212:215], v[86:89]
	v_mfma_f32_16x16x32_bf16 v[78:81], v[164:167], v[212:215], v[78:81]
	v_mfma_f32_16x16x32_bf16 v[126:129], v[160:163], v[192:195], v[126:129]
	v_mfma_f32_16x16x32_bf16 v[122:125], v[168:171], v[192:195], v[122:125]
	v_mfma_f32_16x16x32_bf16 v[118:121], v[160:163], v[200:203], v[118:121]
	v_mfma_f32_16x16x32_bf16 v[110:113], v[168:171], v[200:203], v[110:113]
	v_mfma_f32_16x16x32_bf16 v[102:105], v[160:163], v[208:211], v[102:105]
	v_mfma_f32_16x16x32_bf16 v[94:97], v[168:171], v[208:211], v[94:97]
	v_mfma_f32_16x16x32_bf16 v[86:89], v[160:163], v[216:219], v[86:89]
	v_mfma_f32_16x16x32_bf16 v[78:81], v[168:171], v[216:219], v[78:81]
	s_setprio 0
	s_setprio 1
	v_mfma_f32_16x16x32_bf16 v[114:117], v[172:175], v[188:191], v[114:117]
	v_mfma_f32_16x16x32_bf16 v[106:109], v[180:183], v[188:191], v[106:109]
	v_mfma_f32_16x16x32_bf16 v[98:101], v[172:175], v[196:199], v[98:101]
	v_mfma_f32_16x16x32_bf16 v[90:93], v[180:183], v[196:199], v[90:93]
	v_mfma_f32_16x16x32_bf16 v[82:85], v[172:175], v[204:207], v[82:85]
	v_mfma_f32_16x16x32_bf16 v[74:77], v[180:183], v[204:207], v[74:77]
	v_mfma_f32_16x16x32_bf16 v[70:73], v[172:175], v[212:215], v[70:73]
	v_mfma_f32_16x16x32_bf16 v[66:69], v[180:183], v[212:215], v[66:69]
	v_mfma_f32_16x16x32_bf16 v[114:117], v[176:179], v[192:195], v[114:117]
	v_mfma_f32_16x16x32_bf16 v[106:109], v[184:187], v[192:195], v[106:109]
	v_mfma_f32_16x16x32_bf16 v[98:101], v[176:179], v[200:203], v[98:101]
	v_mfma_f32_16x16x32_bf16 v[90:93], v[184:187], v[200:203], v[90:93]
	v_mfma_f32_16x16x32_bf16 v[82:85], v[176:179], v[208:211], v[82:85]
	v_mfma_f32_16x16x32_bf16 v[74:77], v[184:187], v[208:211], v[74:77]
	v_mfma_f32_16x16x32_bf16 v[70:73], v[176:179], v[216:219], v[70:73]
	v_mfma_f32_16x16x32_bf16 v[66:69], v[184:187], v[216:219], v[66:69]
	s_setprio 0
	s_barrier
	s_add_i32 s62, s48, s39
	v_lshl_add_u64 v[220:221], s[28:29], 0, v[132:133]
	s_mov_b32 m0, s62
	ds_read_b128 v[188:191], v155 offset:16384
	ds_read_b128 v[192:195], v155 offset:17408
	ds_read_b128 v[196:199], v155 offset:18432
	ds_read_b128 v[200:203], v155 offset:19456
	ds_read_b128 v[204:207], v155 offset:20480
	ds_read_b128 v[208:211], v155 offset:21504
	ds_read_b128 v[212:215], v155 offset:22528
	ds_read_b128 v[216:219], v155 offset:23552
	global_load_lds_dwordx4 v[220:221], off
	s_add_i32 m0, s62, 0x2000
	s_add_u32 s62, s28, 0x160000
	v_lshl_add_u64 v[222:223], s[28:29], 0, v[136:137]
	s_addc_u32 s63, s29, 0
	s_add_i32 s65, s49, s39
	global_load_lds_dwordx4 v[222:223], off
	v_lshl_add_u64 v[224:225], s[62:63], 0, v[132:133]
	s_mov_b32 m0, s65
	v_lshl_add_u64 v[226:227], s[30:31], 0, v[134:135]
	global_load_lds_dwordx4 v[224:225], off
	s_cmp_eq_u32 s64, 0
	s_cbranch_scc1 .Lw8_11
	s_waitcnt vmcnt(21)
	s_branch .Lwe_11

.Lwe_11:
	s_waitcnt lgkmcnt(0)
	s_barrier
	s_setprio 1
	s_waitcnt lgkmcnt(0)
	v_mfma_f32_16x16x32_bf16 v[62:65], v[156:159], v[188:191], v[62:65]
	v_mfma_f32_16x16x32_bf16 v[58:61], v[164:167], v[188:191], v[58:61]
	v_lshl_add_u64 v[224:225], s[62:63], 0, v[136:137]
	s_add_i32 m0, s65, 0x2000
	s_nop 0
	global_load_lds_dwordx4 v[224:225], off
	v_mfma_f32_16x16x32_bf16 v[54:57], v[156:159], v[196:199], v[54:57]
	v_mfma_f32_16x16x32_bf16 v[46:49], v[164:167], v[196:199], v[46:49]
	v_mfma_f32_16x16x32_bf16 v[38:41], v[156:159], v[204:207], v[38:41]
	v_mfma_f32_16x16x32_bf16 v[30:33], v[164:167], v[204:207], v[30:33]
	v_mfma_f32_16x16x32_bf16 v[22:25], v[156:159], v[212:215], v[22:25]
	v_mfma_f32_16x16x32_bf16 v[14:17], v[164:167], v[212:215], v[14:17]
	v_mfma_f32_16x16x32_bf16 v[62:65], v[160:163], v[192:195], v[62:65]
	v_mfma_f32_16x16x32_bf16 v[58:61], v[168:171], v[192:195], v[58:61]
	v_lshl_add_u64 v[224:225], s[30:31], 0, v[130:131]
	s_mov_b32 m0, s40
	s_nop 0
	global_load_lds_dwordx4 v[224:225], off
	v_mfma_f32_16x16x32_bf16 v[54:57], v[160:163], v[200:203], v[54:57]
	v_mfma_f32_16x16x32_bf16 v[46:49], v[168:171], v[200:203], v[46:49]
	v_mfma_f32_16x16x32_bf16 v[38:41], v[160:163], v[208:211], v[38:41]
	v_mfma_f32_16x16x32_bf16 v[30:33], v[168:171], v[208:211], v[30:33]
	v_mfma_f32_16x16x32_bf16 v[22:25], v[160:163], v[216:219], v[22:25]
	v_mfma_f32_16x16x32_bf16 v[14:17], v[168:171], v[216:219], v[14:17]
	s_setprio 0
	s_setprio 1
	v_mfma_f32_16x16x32_bf16 v[50:53], v[172:175], v[188:191], v[50:53]
	v_mfma_f32_16x16x32_bf16 v[42:45], v[180:183], v[188:191], v[42:45]
	s_mov_b32 m0, s41
	s_nop 0
	global_load_lds_dwordx4 v[226:227], off
	v_mfma_f32_16x16x32_bf16 v[34:37], v[172:175], v[196:199], v[34:37]
	v_mfma_f32_16x16x32_bf16 v[26:29], v[180:183], v[196:199], v[26:29]
	v_mfma_f32_16x16x32_bf16 v[18:21], v[172:175], v[204:207], v[18:21]
	v_mfma_f32_16x16x32_bf16 v[10:13], v[180:183], v[204:207], v[10:13]
	v_mfma_f32_16x16x32_bf16 v[6:9], v[172:175], v[212:215], v[6:9]
	v_mfma_f32_16x16x32_bf16 v[2:5], v[180:183], v[212:215], v[2:5]
	v_mfma_f32_16x16x32_bf16 v[50:53], v[176:179], v[192:195], v[50:53]
	v_mfma_f32_16x16x32_bf16 v[42:45], v[184:187], v[192:195], v[42:45]
	v_mfma_f32_16x16x32_bf16 v[34:37], v[176:179], v[200:203], v[34:37]
	v_mfma_f32_16x16x32_bf16 v[26:29], v[184:187], v[200:203], v[26:29]
	v_mfma_f32_16x16x32_bf16 v[18:21], v[176:179], v[208:211], v[18:21]
	v_mfma_f32_16x16x32_bf16 v[10:13], v[184:187], v[208:211], v[10:13]
	v_mfma_f32_16x16x32_bf16 v[6:9], v[176:179], v[216:219], v[6:9]
	v_mfma_f32_16x16x32_bf16 v[2:5], v[184:187], v[216:219], v[2:5]
	s_setprio 0
	s_barrier
	s_add_i32 s62, 0, 0x18000
	s_add_i32 s63, 0, 0x1c000
	v_add_u32_e32 v168, s62, v150
	v_add_u32_e32 v184, s63, v150
	ds_read_b128 v[156:159], v168
	ds_read_b128 v[160:163], v168 offset:1024
	ds_read_b128 v[164:167], v168 offset:2048
	ds_read_b128 v[168:171], v168 offset:3072
	ds_read_b128 v[172:175], v184
	ds_read_b128 v[176:179], v184 offset:1024
	ds_read_b128 v[180:183], v184 offset:2048
	ds_read_b128 v[184:187], v184 offset:3072
	s_add_u32 s30, s30, 0x160000
	s_addc_u32 s31, s31, 0
	s_mov_b32 m0, s42
	v_lshl_add_u64 v[228:229], s[30:31], 0, v[130:131]
	ds_read_b128 v[188:191], v155 offset:32768
	ds_read_b128 v[192:195], v155 offset:33792
	ds_read_b128 v[196:199], v155 offset:34816
	ds_read_b128 v[200:203], v155 offset:35840
	ds_read_b128 v[204:207], v155 offset:36864
	ds_read_b128 v[208:211], v155 offset:37888
	ds_read_b128 v[212:215], v155 offset:38912
	ds_read_b128 v[216:219], v155 offset:39936
	global_load_lds_dwordx4 v[228:229], off
	v_lshl_add_u64 v[228:229], s[30:31], 0, v[134:135]
	s_mov_b32 m0, s43
	s_nop 0
	global_load_lds_dwordx4 v[228:229], off
	s_waitcnt vmcnt(8)
	s_waitcnt lgkmcnt(0)
	s_barrier
	s_setprio 1
	s_waitcnt lgkmcnt(0)
	v_mfma_f32_16x16x32_bf16 v[126:129], v[156:159], v[188:191], v[126:129]
	v_mfma_f32_16x16x32_bf16 v[122:125], v[164:167], v[188:191], v[122:125]
	v_mfma_f32_16x16x32_bf16 v[118:121], v[156:159], v[196:199], v[118:121]
	v_mfma_f32_16x16x32_bf16 v[110:113], v[164:167], v[196:199], v[110:113]
	v_mfma_f32_16x16x32_bf16 v[102:105], v[156:159], v[204:207], v[102:105]
	v_mfma_f32_16x16x32_bf16 v[94:97], v[164:167], v[204:207], v[94:97]
	v_mfma_f32_16x16x32_bf16 v[86:89], v[156:159], v[212:215], v[86:89]
	v_mfma_f32_16x16x32_bf16 v[78:81], v[164:167], v[212:215], v[78:81]
	v_mfma_f32_16x16x32_bf16 v[126:129], v[160:163], v[192:195], v[126:129]
	v_mfma_f32_16x16x32_bf16 v[122:125], v[168:171], v[192:195], v[122:125]
	v_mfma_f32_16x16x32_bf16 v[118:121], v[160:163], v[200:203], v[118:121]
	v_mfma_f32_16x16x32_bf16 v[110:113], v[168:171], v[200:203], v[110:113]
	v_mfma_f32_16x16x32_bf16 v[102:105], v[160:163], v[208:211], v[102:105]
	v_mfma_f32_16x16x32_bf16 v[94:97], v[168:171], v[208:211], v[94:97]
	v_mfma_f32_16x16x32_bf16 v[86:89], v[160:163], v[216:219], v[86:89]
	v_mfma_f32_16x16x32_bf16 v[78:81], v[168:171], v[216:219], v[78:81]
	s_setprio 0
	s_setprio 1
	v_mfma_f32_16x16x32_bf16 v[114:117], v[172:175], v[188:191], v[114:117]
	v_mfma_f32_16x16x32_bf16 v[106:109], v[180:183], v[188:191], v[106:109]
	v_mfma_f32_16x16x32_bf16 v[98:101], v[172:175], v[196:199], v[98:101]
	v_mfma_f32_16x16x32_bf16 v[90:93], v[180:183], v[196:199], v[90:93]
	v_mfma_f32_16x16x32_bf16 v[82:85], v[172:175], v[204:207], v[82:85]
	v_mfma_f32_16x16x32_bf16 v[74:77], v[180:183], v[204:207], v[74:77]
	v_mfma_f32_16x16x32_bf16 v[70:73], v[172:175], v[212:215], v[70:73]
	v_mfma_f32_16x16x32_bf16 v[66:69], v[180:183], v[212:215], v[66:69]
	v_mfma_f32_16x16x32_bf16 v[114:117], v[176:179], v[192:195], v[114:117]
	v_mfma_f32_16x16x32_bf16 v[106:109], v[184:187], v[192:195], v[106:109]
	v_mfma_f32_16x16x32_bf16 v[98:101], v[176:179], v[200:203], v[98:101]
	v_mfma_f32_16x16x32_bf16 v[90:93], v[184:187], v[200:203], v[90:93]
	v_mfma_f32_16x16x32_bf16 v[82:85], v[176:179], v[208:211], v[82:85]
	v_mfma_f32_16x16x32_bf16 v[74:77], v[184:187], v[208:211], v[74:77]
	v_mfma_f32_16x16x32_bf16 v[70:73], v[176:179], v[216:219], v[70:73]
	v_mfma_f32_16x16x32_bf16 v[66:69], v[184:187], v[216:219], v[66:69]
	s_setprio 0
	s_barrier
	s_add_i32 s30, s62, s39
	v_lshl_add_u64 v[220:221], v[220:221], 0, s[8:9]
	s_mov_b32 m0, s30
	ds_read_b128 v[188:191], v155 offset:49152
	ds_read_b128 v[192:195], v155 offset:50176
	ds_read_b128 v[196:199], v155 offset:51200
	ds_read_b128 v[200:203], v155 offset:52224
	ds_read_b128 v[204:207], v155 offset:53248
	ds_read_b128 v[208:211], v155 offset:54272
	ds_read_b128 v[212:215], v155 offset:55296
	ds_read_b128 v[216:219], v155 offset:56320
	global_load_lds_dwordx4 v[220:221], off
	s_add_i32 m0, s30, 0x2000
	s_add_u32 s28, s28, 0x160080
	v_lshl_add_u64 v[220:221], v[222:223], 0, s[8:9]
	s_addc_u32 s29, s29, 0
	s_add_i32 s30, s63, s39
	global_load_lds_dwordx4 v[220:221], off
	v_lshl_add_u64 v[220:221], s[28:29], 0, v[132:133]
	s_mov_b32 m0, s30
	s_nop 0
	global_load_lds_dwordx4 v[220:221], off
	s_waitcnt vmcnt(5)
	s_waitcnt lgkmcnt(0)
	s_barrier
	s_setprio 1
	s_waitcnt lgkmcnt(0)
	v_mfma_f32_16x16x32_bf16 v[62:65], v[156:159], v[188:191], v[62:65]
	v_mfma_f32_16x16x32_bf16 v[58:61], v[164:167], v[188:191], v[58:61]
	v_lshl_add_u64 v[220:221], s[28:29], 0, v[136:137]
	s_add_i32 m0, s30, 0x2000
	s_nop 0
	global_load_lds_dwordx4 v[220:221], off
	v_mfma_f32_16x16x32_bf16 v[54:57], v[156:159], v[196:199], v[54:57]
	v_mfma_f32_16x16x32_bf16 v[46:49], v[164:167], v[196:199], v[46:49]
	v_mfma_f32_16x16x32_bf16 v[38:41], v[156:159], v[204:207], v[38:41]
	v_mfma_f32_16x16x32_bf16 v[30:33], v[164:167], v[204:207], v[30:33]
	v_mfma_f32_16x16x32_bf16 v[22:25], v[156:159], v[212:215], v[22:25]
	v_mfma_f32_16x16x32_bf16 v[14:17], v[164:167], v[212:215], v[14:17]
	v_mfma_f32_16x16x32_bf16 v[62:65], v[160:163], v[192:195], v[62:65]
	v_mfma_f32_16x16x32_bf16 v[58:61], v[168:171], v[192:195], v[58:61]
	v_lshl_add_u64 v[220:221], v[224:225], 0, s[8:9]
	s_mov_b32 m0, s44
	s_nop 0
	global_load_lds_dwordx4 v[220:221], off
	v_mfma_f32_16x16x32_bf16 v[54:57], v[160:163], v[200:203], v[54:57]
	v_mfma_f32_16x16x32_bf16 v[46:49], v[168:171], v[200:203], v[46:49]
	v_mfma_f32_16x16x32_bf16 v[38:41], v[160:163], v[208:211], v[38:41]
	v_mfma_f32_16x16x32_bf16 v[30:33], v[168:171], v[208:211], v[30:33]
	v_mfma_f32_16x16x32_bf16 v[22:25], v[160:163], v[216:219], v[22:25]
	v_mfma_f32_16x16x32_bf16 v[14:17], v[168:171], v[216:219], v[14:17]
	s_setprio 0
	s_setprio 1
	v_mfma_f32_16x16x32_bf16 v[50:53], v[172:175], v[188:191], v[50:53]
	v_mfma_f32_16x16x32_bf16 v[42:45], v[180:183], v[188:191], v[42:45]
	v_lshl_add_u64 v[220:221], v[226:227], 0, s[8:9]
	s_mov_b32 m0, s45
	s_nop 0
	global_load_lds_dwordx4 v[220:221], off
	v_mfma_f32_16x16x32_bf16 v[34:37], v[172:175], v[196:199], v[34:37]
	v_mfma_f32_16x16x32_bf16 v[26:29], v[180:183], v[196:199], v[26:29]
	v_mfma_f32_16x16x32_bf16 v[18:21], v[172:175], v[204:207], v[18:21]
	v_mfma_f32_16x16x32_bf16 v[10:13], v[180:183], v[204:207], v[10:13]
	v_mfma_f32_16x16x32_bf16 v[6:9], v[172:175], v[212:215], v[6:9]
	v_mfma_f32_16x16x32_bf16 v[2:5], v[180:183], v[212:215], v[2:5]
	v_mfma_f32_16x16x32_bf16 v[50:53], v[176:179], v[192:195], v[50:53]
	v_mfma_f32_16x16x32_bf16 v[42:45], v[184:187], v[192:195], v[42:45]
	v_mfma_f32_16x16x32_bf16 v[34:37], v[176:179], v[200:203], v[34:37]
	v_mfma_f32_16x16x32_bf16 v[26:29], v[184:187], v[200:203], v[26:29]
	v_mfma_f32_16x16x32_bf16 v[18:21], v[176:179], v[208:211], v[18:21]
	v_mfma_f32_16x16x32_bf16 v[10:13], v[184:187], v[208:211], v[10:13]
	v_mfma_f32_16x16x32_bf16 v[6:9], v[176:179], v[216:219], v[6:9]
	v_mfma_f32_16x16x32_bf16 v[2:5], v[184:187], v[216:219], v[2:5]
	s_setprio 0
	s_barrier
	s_add_i32 s61, s61, 2
	s_add_u32 s26, s26, 0x100
	s_addc_u32 s27, s27, 0
	s_cmpk_gt_u32 s61, 0x55
	s_cbranch_scc0 .LBB0_1417
	s_and_b64 vcc, exec, s[10:11]
	s_cbranch_vccz .LBB0_1420
	s_barrier

.Lwe_12:
	s_waitcnt lgkmcnt(0)
	s_barrier
	s_setprio 1
	s_waitcnt lgkmcnt(0)
	v_mfma_f32_16x16x32_bf16 v[126:129], v[158:161], v[190:193], v[126:129]
	v_mfma_f32_16x16x32_bf16 v[122:125], v[166:169], v[190:193], v[122:125]
	v_mfma_f32_16x16x32_bf16 v[118:121], v[158:161], v[198:201], v[118:121]
	v_mfma_f32_16x16x32_bf16 v[110:113], v[166:169], v[198:201], v[110:113]
	v_mfma_f32_16x16x32_bf16 v[102:105], v[158:161], v[206:209], v[102:105]
	v_mfma_f32_16x16x32_bf16 v[94:97], v[166:169], v[206:209], v[94:97]
	v_mfma_f32_16x16x32_bf16 v[86:89], v[158:161], v[214:217], v[86:89]
	v_mfma_f32_16x16x32_bf16 v[78:81], v[166:169], v[214:217], v[78:81]
	v_mfma_f32_16x16x32_bf16 v[126:129], v[162:165], v[194:197], v[126:129]
	v_mfma_f32_16x16x32_bf16 v[122:125], v[170:173], v[194:197], v[122:125]
	v_mfma_f32_16x16x32_bf16 v[118:121], v[162:165], v[202:205], v[118:121]
	v_mfma_f32_16x16x32_bf16 v[110:113], v[170:173], v[202:205], v[110:113]
	v_mfma_f32_16x16x32_bf16 v[102:105], v[162:165], v[210:213], v[102:105]
	v_mfma_f32_16x16x32_bf16 v[94:97], v[170:173], v[210:213], v[94:97]
	v_mfma_f32_16x16x32_bf16 v[86:89], v[162:165], v[218:221], v[86:89]
	v_mfma_f32_16x16x32_bf16 v[78:81], v[170:173], v[218:221], v[78:81]
	s_setprio 0
	s_setprio 1
	v_mfma_f32_16x16x32_bf16 v[114:117], v[174:177], v[190:193], v[114:117]
	v_mfma_f32_16x16x32_bf16 v[106:109], v[182:185], v[190:193], v[106:109]
	v_mfma_f32_16x16x32_bf16 v[98:101], v[174:177], v[198:201], v[98:101]
	v_mfma_f32_16x16x32_bf16 v[90:93], v[182:185], v[198:201], v[90:93]
	v_mfma_f32_16x16x32_bf16 v[82:85], v[174:177], v[206:209], v[82:85]
	v_mfma_f32_16x16x32_bf16 v[74:77], v[182:185], v[206:209], v[74:77]
	v_mfma_f32_16x16x32_bf16 v[70:73], v[174:177], v[214:217], v[70:73]
	v_mfma_f32_16x16x32_bf16 v[66:69], v[182:185], v[214:217], v[66:69]
	v_mfma_f32_16x16x32_bf16 v[114:117], v[178:181], v[194:197], v[114:117]
	v_mfma_f32_16x16x32_bf16 v[106:109], v[186:189], v[194:197], v[106:109]
	v_mfma_f32_16x16x32_bf16 v[98:101], v[178:181], v[202:205], v[98:101]
	v_mfma_f32_16x16x32_bf16 v[90:93], v[186:189], v[202:205], v[90:93]
	v_mfma_f32_16x16x32_bf16 v[82:85], v[178:181], v[210:213], v[82:85]
	v_mfma_f32_16x16x32_bf16 v[74:77], v[186:189], v[210:213], v[74:77]
	v_mfma_f32_16x16x32_bf16 v[70:73], v[178:181], v[218:221], v[70:73]
	v_mfma_f32_16x16x32_bf16 v[66:69], v[186:189], v[218:221], v[66:69]
	s_setprio 0
	s_barrier
	s_add_i32 s70, s60, s48
	v_lshl_add_u64 v[222:223], s[40:41], 0, v[134:135]
	s_mov_b32 m0, s70
	ds_read_b128 v[190:193], v156 offset:16384
	ds_read_b128 v[194:197], v156 offset:17408
	ds_read_b128 v[198:201], v156 offset:18432
	ds_read_b128 v[202:205], v156 offset:19456
	ds_read_b128 v[206:209], v156 offset:20480
	ds_read_b128 v[210:213], v156 offset:21504
	ds_read_b128 v[214:217], v156 offset:22528
	ds_read_b128 v[218:221], v156 offset:23552
	global_load_lds_dwordx4 v[222:223], off
	s_add_i32 m0, s70, 0x2000
	s_add_u32 s70, s40, 0x80000
	v_lshl_add_u64 v[224:225], s[40:41], 0, v[130:131]
	s_addc_u32 s71, s41, 0
	s_add_i32 s73, s61, s48
	global_load_lds_dwordx4 v[224:225], off
	v_lshl_add_u64 v[226:227], s[70:71], 0, v[134:135]
	s_mov_b32 m0, s73
	v_lshl_add_u64 v[228:229], s[42:43], 0, v[132:133]
	global_load_lds_dwordx4 v[226:227], off
	s_cmp_eq_u32 s72, 0
	s_cbranch_scc1 .Lw8_13
	s_waitcnt vmcnt(21)
	s_branch .Lwe_13

.Lwe_13:
	s_waitcnt lgkmcnt(0)
	s_barrier
	s_setprio 1
	s_waitcnt lgkmcnt(0)
	v_mfma_f32_16x16x32_bf16 v[62:65], v[158:161], v[190:193], v[62:65]
	v_mfma_f32_16x16x32_bf16 v[58:61], v[166:169], v[190:193], v[58:61]
	v_lshl_add_u64 v[226:227], s[70:71], 0, v[130:131]
	s_add_i32 m0, s73, 0x2000
	s_nop 0
	global_load_lds_dwordx4 v[226:227], off
	v_mfma_f32_16x16x32_bf16 v[54:57], v[158:161], v[198:201], v[54:57]
	v_mfma_f32_16x16x32_bf16 v[46:49], v[166:169], v[198:201], v[46:49]
	v_mfma_f32_16x16x32_bf16 v[38:41], v[158:161], v[206:209], v[38:41]
	v_mfma_f32_16x16x32_bf16 v[30:33], v[166:169], v[206:209], v[30:33]
	v_mfma_f32_16x16x32_bf16 v[22:25], v[158:161], v[214:217], v[22:25]
	v_mfma_f32_16x16x32_bf16 v[14:17], v[166:169], v[214:217], v[14:17]
	v_mfma_f32_16x16x32_bf16 v[62:65], v[162:165], v[194:197], v[62:65]
	v_mfma_f32_16x16x32_bf16 v[58:61], v[170:173], v[194:197], v[58:61]
	v_lshl_add_u64 v[226:227], s[42:43], 0, v[136:137]
	s_mov_b32 m0, s51
	s_nop 0
	global_load_lds_dwordx4 v[226:227], off
	v_mfma_f32_16x16x32_bf16 v[54:57], v[162:165], v[202:205], v[54:57]
	v_mfma_f32_16x16x32_bf16 v[46:49], v[170:173], v[202:205], v[46:49]
	v_mfma_f32_16x16x32_bf16 v[38:41], v[162:165], v[210:213], v[38:41]
	v_mfma_f32_16x16x32_bf16 v[30:33], v[170:173], v[210:213], v[30:33]
	v_mfma_f32_16x16x32_bf16 v[22:25], v[162:165], v[218:221], v[22:25]
	v_mfma_f32_16x16x32_bf16 v[14:17], v[170:173], v[218:221], v[14:17]
	s_setprio 0
	s_setprio 1
	v_mfma_f32_16x16x32_bf16 v[50:53], v[174:177], v[190:193], v[50:53]
	v_mfma_f32_16x16x32_bf16 v[42:45], v[182:185], v[190:193], v[42:45]
	s_mov_b32 m0, s52
	s_nop 0
	global_load_lds_dwordx4 v[228:229], off
	v_mfma_f32_16x16x32_bf16 v[34:37], v[174:177], v[198:201], v[34:37]
	v_mfma_f32_16x16x32_bf16 v[26:29], v[182:185], v[198:201], v[26:29]
	v_mfma_f32_16x16x32_bf16 v[18:21], v[174:177], v[206:209], v[18:21]
	v_mfma_f32_16x16x32_bf16 v[10:13], v[182:185], v[206:209], v[10:13]
	v_mfma_f32_16x16x32_bf16 v[6:9], v[174:177], v[214:217], v[6:9]
	v_mfma_f32_16x16x32_bf16 v[2:5], v[182:185], v[214:217], v[2:5]
	v_mfma_f32_16x16x32_bf16 v[50:53], v[178:181], v[194:197], v[50:53]
	v_mfma_f32_16x16x32_bf16 v[42:45], v[186:189], v[194:197], v[42:45]
	v_mfma_f32_16x16x32_bf16 v[34:37], v[178:181], v[202:205], v[34:37]
	v_mfma_f32_16x16x32_bf16 v[26:29], v[186:189], v[202:205], v[26:29]
	v_mfma_f32_16x16x32_bf16 v[18:21], v[178:181], v[210:213], v[18:21]
	v_mfma_f32_16x16x32_bf16 v[10:13], v[186:189], v[210:213], v[10:13]
	v_mfma_f32_16x16x32_bf16 v[6:9], v[178:181], v[218:221], v[6:9]
	v_mfma_f32_16x16x32_bf16 v[2:5], v[186:189], v[218:221], v[2:5]
	s_setprio 0
	s_barrier
	s_add_i32 s70, 0, 0x18000
	v_add_u32_e32 v157, s70, v150
	s_add_i32 s71, 0, 0x1c000
	ds_read_b128 v[158:161], v157
	ds_read_b128 v[162:165], v157 offset:1024
	ds_read_b128 v[166:169], v157 offset:2048
	ds_read_b128 v[170:173], v157 offset:3072
	v_add_u32_e32 v157, s71, v150
	ds_read_b128 v[174:177], v157
	ds_read_b128 v[178:181], v157 offset:1024
	ds_read_b128 v[182:185], v157 offset:2048
	ds_read_b128 v[186:189], v157 offset:3072
	s_add_u32 s42, s42, 0x80000
	s_addc_u32 s43, s43, 0
	s_mov_b32 m0, s53
	v_lshl_add_u64 v[230:231], s[42:43], 0, v[136:137]
	ds_read_b128 v[190:193], v156 offset:32768
	ds_read_b128 v[194:197], v156 offset:33792
	ds_read_b128 v[198:201], v156 offset:34816
	ds_read_b128 v[202:205], v156 offset:35840
	ds_read_b128 v[206:209], v156 offset:36864
	ds_read_b128 v[210:213], v156 offset:37888
	ds_read_b128 v[214:217], v156 offset:38912
	ds_read_b128 v[218:221], v156 offset:39936
	global_load_lds_dwordx4 v[230:231], off
	v_lshl_add_u64 v[230:231], s[42:43], 0, v[132:133]
	s_mov_b32 m0, s54
	s_nop 0
	global_load_lds_dwordx4 v[230:231], off
	s_waitcnt vmcnt(8)
	s_waitcnt lgkmcnt(0)
	s_barrier
	s_setprio 1
	s_waitcnt lgkmcnt(0)
	v_mfma_f32_16x16x32_bf16 v[126:129], v[158:161], v[190:193], v[126:129]
	v_mfma_f32_16x16x32_bf16 v[122:125], v[166:169], v[190:193], v[122:125]
	v_mfma_f32_16x16x32_bf16 v[118:121], v[158:161], v[198:201], v[118:121]
	v_mfma_f32_16x16x32_bf16 v[110:113], v[166:169], v[198:201], v[110:113]
	v_mfma_f32_16x16x32_bf16 v[102:105], v[158:161], v[206:209], v[102:105]
	v_mfma_f32_16x16x32_bf16 v[94:97], v[166:169], v[206:209], v[94:97]
	v_mfma_f32_16x16x32_bf16 v[86:89], v[158:161], v[214:217], v[86:89]
	v_mfma_f32_16x16x32_bf16 v[78:81], v[166:169], v[214:217], v[78:81]
	v_mfma_f32_16x16x32_bf16 v[126:129], v[162:165], v[194:197], v[126:129]
	v_mfma_f32_16x16x32_bf16 v[122:125], v[170:173], v[194:197], v[122:125]
	v_mfma_f32_16x16x32_bf16 v[118:121], v[162:165], v[202:205], v[118:121]
	v_mfma_f32_16x16x32_bf16 v[110:113], v[170:173], v[202:205], v[110:113]
	v_mfma_f32_16x16x32_bf16 v[102:105], v[162:165], v[210:213], v[102:105]
	v_mfma_f32_16x16x32_bf16 v[94:97], v[170:173], v[210:213], v[94:97]
	v_mfma_f32_16x16x32_bf16 v[86:89], v[162:165], v[218:221], v[86:89]
	v_mfma_f32_16x16x32_bf16 v[78:81], v[170:173], v[218:221], v[78:81]
	s_setprio 0
	s_setprio 1
	v_mfma_f32_16x16x32_bf16 v[114:117], v[174:177], v[190:193], v[114:117]
	v_mfma_f32_16x16x32_bf16 v[106:109], v[182:185], v[190:193], v[106:109]
	v_mfma_f32_16x16x32_bf16 v[98:101], v[174:177], v[198:201], v[98:101]
	v_mfma_f32_16x16x32_bf16 v[90:93], v[182:185], v[198:201], v[90:93]
	v_mfma_f32_16x16x32_bf16 v[82:85], v[174:177], v[206:209], v[82:85]
	v_mfma_f32_16x16x32_bf16 v[74:77], v[182:185], v[206:209], v[74:77]
	v_mfma_f32_16x16x32_bf16 v[70:73], v[174:177], v[214:217], v[70:73]
	v_mfma_f32_16x16x32_bf16 v[66:69], v[182:185], v[214:217], v[66:69]
	v_mfma_f32_16x16x32_bf16 v[114:117], v[178:181], v[194:197], v[114:117]
	v_mfma_f32_16x16x32_bf16 v[106:109], v[186:189], v[194:197], v[106:109]
	v_mfma_f32_16x16x32_bf16 v[98:101], v[178:181], v[202:205], v[98:101]
	v_mfma_f32_16x16x32_bf16 v[90:93], v[186:189], v[202:205], v[90:93]
	v_mfma_f32_16x16x32_bf16 v[82:85], v[178:181], v[210:213], v[82:85]
	v_mfma_f32_16x16x32_bf16 v[74:77], v[186:189], v[210:213], v[74:77]
	v_mfma_f32_16x16x32_bf16 v[70:73], v[178:181], v[218:221], v[70:73]
	v_mfma_f32_16x16x32_bf16 v[66:69], v[186:189], v[218:221], v[66:69]
	s_setprio 0
	s_barrier
	s_add_i32 s42, s70, s48
	v_lshl_add_u64 v[222:223], v[222:223], 0, s[12:13]
	s_mov_b32 m0, s42
	ds_read_b128 v[190:193], v156 offset:49152
	ds_read_b128 v[194:197], v156 offset:50176
	ds_read_b128 v[198:201], v156 offset:51200
	ds_read_b128 v[202:205], v156 offset:52224
	ds_read_b128 v[206:209], v156 offset:53248
	ds_read_b128 v[210:213], v156 offset:54272
	ds_read_b128 v[214:217], v156 offset:55296
	ds_read_b128 v[218:221], v156 offset:56320
	global_load_lds_dwordx4 v[222:223], off
	s_add_i32 m0, s42, 0x2000
	s_add_u32 s40, s40, 0x80080
	v_lshl_add_u64 v[222:223], v[224:225], 0, s[12:13]
	s_addc_u32 s41, s41, 0
	s_add_i32 s42, s71, s48
	global_load_lds_dwordx4 v[222:223], off
	v_lshl_add_u64 v[222:223], s[40:41], 0, v[134:135]
	s_mov_b32 m0, s42
	s_nop 0
	global_load_lds_dwordx4 v[222:223], off
	s_waitcnt vmcnt(5)
	s_waitcnt lgkmcnt(0)
	s_barrier
	s_setprio 1
	s_waitcnt lgkmcnt(0)
	v_mfma_f32_16x16x32_bf16 v[62:65], v[158:161], v[190:193], v[62:65]
	v_mfma_f32_16x16x32_bf16 v[58:61], v[166:169], v[190:193], v[58:61]
	v_lshl_add_u64 v[222:223], s[40:41], 0, v[130:131]
	s_add_i32 m0, s42, 0x2000
	s_nop 0
	global_load_lds_dwordx4 v[222:223], off
	v_mfma_f32_16x16x32_bf16 v[54:57], v[158:161], v[198:201], v[54:57]
	v_mfma_f32_16x16x32_bf16 v[46:49], v[166:169], v[198:201], v[46:49]
	v_mfma_f32_16x16x32_bf16 v[38:41], v[158:161], v[206:209], v[38:41]
	v_mfma_f32_16x16x32_bf16 v[30:33], v[166:169], v[206:209], v[30:33]
	v_mfma_f32_16x16x32_bf16 v[22:25], v[158:161], v[214:217], v[22:25]
	v_mfma_f32_16x16x32_bf16 v[14:17], v[166:169], v[214:217], v[14:17]
	v_mfma_f32_16x16x32_bf16 v[62:65], v[162:165], v[194:197], v[62:65]
	v_mfma_f32_16x16x32_bf16 v[58:61], v[170:173], v[194:197], v[58:61]
	v_lshl_add_u64 v[222:223], v[226:227], 0, s[12:13]
	s_mov_b32 m0, s56
	s_nop 0
	global_load_lds_dwordx4 v[222:223], off
	v_mfma_f32_16x16x32_bf16 v[54:57], v[162:165], v[202:205], v[54:57]
	v_mfma_f32_16x16x32_bf16 v[46:49], v[170:173], v[202:205], v[46:49]
	v_mfma_f32_16x16x32_bf16 v[38:41], v[162:165], v[210:213], v[38:41]
	v_mfma_f32_16x16x32_bf16 v[30:33], v[170:173], v[210:213], v[30:33]
	v_mfma_f32_16x16x32_bf16 v[22:25], v[162:165], v[218:221], v[22:25]
	v_mfma_f32_16x16x32_bf16 v[14:17], v[170:173], v[218:221], v[14:17]
	s_setprio 0
	s_setprio 1
	v_mfma_f32_16x16x32_bf16 v[50:53], v[174:177], v[190:193], v[50:53]
	v_mfma_f32_16x16x32_bf16 v[42:45], v[182:185], v[190:193], v[42:45]
	v_lshl_add_u64 v[222:223], v[228:229], 0, s[12:13]
	s_mov_b32 m0, s57
	s_nop 0
	global_load_lds_dwordx4 v[222:223], off
	v_mfma_f32_16x16x32_bf16 v[34:37], v[174:177], v[198:201], v[34:37]
	v_mfma_f32_16x16x32_bf16 v[26:29], v[182:185], v[198:201], v[26:29]
	v_mfma_f32_16x16x32_bf16 v[18:21], v[174:177], v[206:209], v[18:21]
	v_mfma_f32_16x16x32_bf16 v[10:13], v[182:185], v[206:209], v[10:13]
	v_mfma_f32_16x16x32_bf16 v[6:9], v[174:177], v[214:217], v[6:9]
	v_mfma_f32_16x16x32_bf16 v[2:5], v[182:185], v[214:217], v[2:5]
	v_mfma_f32_16x16x32_bf16 v[50:53], v[178:181], v[194:197], v[50:53]
	v_mfma_f32_16x16x32_bf16 v[42:45], v[186:189], v[194:197], v[42:45]
	v_mfma_f32_16x16x32_bf16 v[34:37], v[178:181], v[202:205], v[34:37]
	v_mfma_f32_16x16x32_bf16 v[26:29], v[186:189], v[202:205], v[26:29]
	v_mfma_f32_16x16x32_bf16 v[18:21], v[178:181], v[210:213], v[18:21]
	v_mfma_f32_16x16x32_bf16 v[10:13], v[186:189], v[210:213], v[10:13]
	v_mfma_f32_16x16x32_bf16 v[6:9], v[178:181], v[218:221], v[6:9]
	v_mfma_f32_16x16x32_bf16 v[2:5], v[186:189], v[218:221], v[2:5]
	s_setprio 0
	s_barrier
	s_add_i32 s69, s69, 2
	s_add_u32 s38, s38, 0x100
	s_addc_u32 s39, s39, 0
	s_cmp_gt_u32 s69, 29
	s_cbranch_scc0 .LBB0_1587
	s_and_b64 vcc, exec, s[14:15]
	s_cbranch_vccnz .LBB0_1592
	s_mov_b64 s[30:31], -1
	s_and_b64 vcc, exec, s[34:35]
	s_cbranch_vccnz .LBB0_1593
